# conv units: each 31-tap FIR chain split into two interleaved accumulation chains (even/odd taps) joined by one add
# baseline (speedup 1.0000x reference)
.LBB0_1100:
	s_or_b64 exec, exec, s[0:1]
	s_xor_b64 s[18:19], s[14:15], -1
	v_cndmask_b32_e64 v132, 0, 1, s[18:19]
	s_waitcnt vmcnt(0)
	v_lshlrev_b32_e32 v130, 16, v131
	v_cmp_ne_u32_e64 s[0:1], 1, v132
	s_andn2_b64 vcc, exec, s[18:19]
	v_and_b32_e32 v131, 0xffff0000, v131
	s_cbranch_vccnz .LBB0_1132
	v_pk_fma_f32 v[128:129], v[4:5], v[128:129], v[66:67]
	v_lshl_add_u32 v132, s43, 16, v139
	v_pk_mul_f32 v[176:177], v[6:7], v[126:127]
	v_add3_u32 v132, v132, v2, s64
	v_pk_fma_f32 v[128:129], v[8:9], v[124:125], v[128:129]
	v_pk_fma_f32 v[176:177], v[28:29], v[122:123], v[176:177]
	v_pk_fma_f32 v[128:129], v[10:11], v[120:121], v[128:129]
	v_pk_fma_f32 v[176:177], v[12:13], v[118:119], v[176:177]
	v_pk_fma_f32 v[128:129], v[14:15], v[116:117], v[128:129]
	v_pk_fma_f32 v[176:177], v[30:31], v[114:115], v[176:177]
	v_pk_fma_f32 v[128:129], v[16:17], v[112:113], v[128:129]
	v_pk_fma_f32 v[176:177], v[18:19], v[110:111], v[176:177]
	v_pk_fma_f32 v[128:129], v[20:21], v[108:109], v[128:129]
	v_pk_fma_f32 v[176:177], v[32:33], v[106:107], v[176:177]
	v_pk_fma_f32 v[128:129], v[22:23], v[104:105], v[128:129]
	v_pk_fma_f32 v[176:177], v[24:25], v[102:103], v[176:177]
	v_pk_fma_f32 v[128:129], v[26:27], v[100:101], v[128:129]
	v_pk_fma_f32 v[176:177], v[34:35], v[98:99], v[176:177]
	v_pk_fma_f32 v[128:129], v[36:37], v[96:97], v[128:129]
	v_pk_fma_f32 v[176:177], v[38:39], v[94:95], v[176:177]
	v_pk_fma_f32 v[128:129], v[40:41], v[92:93], v[128:129]
	v_pk_fma_f32 v[176:177], v[58:59], v[90:91], v[176:177]
	v_pk_fma_f32 v[128:129], v[42:43], v[88:89], v[128:129]
	v_pk_fma_f32 v[176:177], v[44:45], v[86:87], v[176:177]
	v_pk_fma_f32 v[128:129], v[46:47], v[84:85], v[128:129]
	v_pk_fma_f32 v[176:177], v[60:61], v[82:83], v[176:177]
	v_pk_fma_f32 v[128:129], v[48:49], v[80:81], v[128:129]
	v_pk_fma_f32 v[176:177], v[50:51], v[78:79], v[176:177]
	v_pk_fma_f32 v[128:129], v[52:53], v[76:77], v[128:129]
	v_pk_fma_f32 v[176:177], v[62:63], v[74:75], v[176:177]
	v_pk_fma_f32 v[128:129], v[54:55], v[70:71], v[128:129]
	v_pk_fma_f32 v[176:177], v[56:57], v[134:135], v[176:177]
	v_pk_fma_f32 v[128:129], v[64:65], v[130:131], v[128:129]
	s_nop 0
	v_pk_add_f32 v[128:129], v[128:129], v[176:177]
	ds_write_b64 v132, v[128:129]
	v_lshlrev_b32_e32 v132, 16, v133
	s_and_b64 vcc, exec, s[0:1]
	v_and_b32_e32 v133, 0xffff0000, v133
	s_cbranch_vccz .LBB0_1133

.LBB0_1103:
	v_pk_fma_f32 v[124:125], v[4:5], v[124:125], v[66:67]
	v_lshl_add_u32 v126, s51, 11, v139
	v_pk_mul_f32 v[176:177], v[6:7], v[122:123]
	v_add3_u32 v126, v126, v2, s64
	v_pk_fma_f32 v[124:125], v[8:9], v[120:121], v[124:125]
	v_pk_fma_f32 v[176:177], v[28:29], v[118:119], v[176:177]
	v_pk_fma_f32 v[124:125], v[10:11], v[116:117], v[124:125]
	v_pk_fma_f32 v[176:177], v[12:13], v[114:115], v[176:177]
	v_pk_fma_f32 v[124:125], v[14:15], v[112:113], v[124:125]
	v_pk_fma_f32 v[176:177], v[30:31], v[110:111], v[176:177]
	v_pk_fma_f32 v[124:125], v[16:17], v[108:109], v[124:125]
	v_pk_fma_f32 v[176:177], v[18:19], v[106:107], v[176:177]
	v_pk_fma_f32 v[124:125], v[20:21], v[104:105], v[124:125]
	v_pk_fma_f32 v[176:177], v[32:33], v[102:103], v[176:177]
	v_pk_fma_f32 v[124:125], v[22:23], v[100:101], v[124:125]
	v_pk_fma_f32 v[176:177], v[24:25], v[98:99], v[176:177]
	v_pk_fma_f32 v[124:125], v[26:27], v[96:97], v[124:125]
	v_pk_fma_f32 v[176:177], v[34:35], v[94:95], v[176:177]
	v_pk_fma_f32 v[124:125], v[36:37], v[92:93], v[124:125]
	v_pk_fma_f32 v[176:177], v[38:39], v[90:91], v[176:177]
	v_pk_fma_f32 v[124:125], v[40:41], v[88:89], v[124:125]
	v_pk_fma_f32 v[176:177], v[58:59], v[86:87], v[176:177]
	v_pk_fma_f32 v[124:125], v[42:43], v[84:85], v[124:125]
	v_pk_fma_f32 v[176:177], v[44:45], v[82:83], v[176:177]
	v_pk_fma_f32 v[124:125], v[46:47], v[80:81], v[124:125]
	v_pk_fma_f32 v[176:177], v[60:61], v[78:79], v[176:177]
	v_pk_fma_f32 v[124:125], v[48:49], v[76:77], v[124:125]
	v_pk_fma_f32 v[176:177], v[50:51], v[74:75], v[176:177]
	v_pk_fma_f32 v[124:125], v[52:53], v[70:71], v[124:125]
	v_pk_fma_f32 v[176:177], v[62:63], v[134:135], v[176:177]
	v_pk_fma_f32 v[124:125], v[54:55], v[130:131], v[124:125]
	v_pk_fma_f32 v[176:177], v[56:57], v[132:133], v[176:177]
	v_pk_fma_f32 v[124:125], v[64:65], v[128:129], v[124:125]
	s_nop 0
	v_pk_add_f32 v[124:125], v[124:125], v[176:177]
	ds_write_b64 v126, v[124:125]
	v_lshlrev_b32_e32 v126, 16, v171
	s_and_b64 vcc, exec, s[0:1]
	v_and_b32_e32 v127, 0xffff0000, v171
	s_cbranch_vccz .LBB0_1135

.LBB0_1105:
	v_pk_fma_f32 v[120:121], v[4:5], v[120:121], v[66:67]
	v_lshl_add_u32 v122, s49, 11, v139
	v_pk_mul_f32 v[176:177], v[6:7], v[118:119]
	v_add3_u32 v122, v122, v2, s64
	v_pk_fma_f32 v[120:121], v[8:9], v[116:117], v[120:121]
	v_pk_fma_f32 v[176:177], v[28:29], v[114:115], v[176:177]
	v_pk_fma_f32 v[120:121], v[10:11], v[112:113], v[120:121]
	v_pk_fma_f32 v[176:177], v[12:13], v[110:111], v[176:177]
	v_pk_fma_f32 v[120:121], v[14:15], v[108:109], v[120:121]
	v_pk_fma_f32 v[176:177], v[30:31], v[106:107], v[176:177]
	v_pk_fma_f32 v[120:121], v[16:17], v[104:105], v[120:121]
	v_pk_fma_f32 v[176:177], v[18:19], v[102:103], v[176:177]
	v_pk_fma_f32 v[120:121], v[20:21], v[100:101], v[120:121]
	v_pk_fma_f32 v[176:177], v[32:33], v[98:99], v[176:177]
	v_pk_fma_f32 v[120:121], v[22:23], v[96:97], v[120:121]
	v_pk_fma_f32 v[176:177], v[24:25], v[94:95], v[176:177]
	v_pk_fma_f32 v[120:121], v[26:27], v[92:93], v[120:121]
	v_pk_fma_f32 v[176:177], v[34:35], v[90:91], v[176:177]
	v_pk_fma_f32 v[120:121], v[36:37], v[88:89], v[120:121]
	v_pk_fma_f32 v[176:177], v[38:39], v[86:87], v[176:177]
	v_pk_fma_f32 v[120:121], v[40:41], v[84:85], v[120:121]
	v_pk_fma_f32 v[176:177], v[58:59], v[82:83], v[176:177]
	v_pk_fma_f32 v[120:121], v[42:43], v[80:81], v[120:121]
	v_pk_fma_f32 v[176:177], v[44:45], v[78:79], v[176:177]
	v_pk_fma_f32 v[120:121], v[46:47], v[76:77], v[120:121]
	v_pk_fma_f32 v[176:177], v[60:61], v[74:75], v[176:177]
	v_pk_fma_f32 v[120:121], v[48:49], v[70:71], v[120:121]
	v_pk_fma_f32 v[176:177], v[50:51], v[134:135], v[176:177]
	v_pk_fma_f32 v[120:121], v[52:53], v[130:131], v[120:121]
	v_pk_fma_f32 v[176:177], v[62:63], v[132:133], v[176:177]
	v_pk_fma_f32 v[120:121], v[54:55], v[128:129], v[120:121]
	v_pk_fma_f32 v[176:177], v[56:57], v[126:127], v[176:177]
	v_pk_fma_f32 v[120:121], v[64:65], v[124:125], v[120:121]
	s_nop 0
	v_pk_add_f32 v[120:121], v[120:121], v[176:177]
	ds_write_b64 v122, v[120:121]
	v_lshlrev_b32_e32 v122, 16, v169
	s_and_b64 vcc, exec, s[0:1]
	v_and_b32_e32 v123, 0xffff0000, v169
	s_cbranch_vccz .LBB0_1137

.LBB0_1107:
	v_pk_fma_f32 v[116:117], v[4:5], v[116:117], v[66:67]
	v_lshl_add_u32 v118, s47, 11, v139
	v_pk_mul_f32 v[176:177], v[6:7], v[114:115]
	v_add3_u32 v118, v118, v2, s64
	v_pk_fma_f32 v[116:117], v[8:9], v[112:113], v[116:117]
	v_pk_fma_f32 v[176:177], v[28:29], v[110:111], v[176:177]
	v_pk_fma_f32 v[116:117], v[10:11], v[108:109], v[116:117]
	v_pk_fma_f32 v[176:177], v[12:13], v[106:107], v[176:177]
	v_pk_fma_f32 v[116:117], v[14:15], v[104:105], v[116:117]
	v_pk_fma_f32 v[176:177], v[30:31], v[102:103], v[176:177]
	v_pk_fma_f32 v[116:117], v[16:17], v[100:101], v[116:117]
	v_pk_fma_f32 v[176:177], v[18:19], v[98:99], v[176:177]
	v_pk_fma_f32 v[116:117], v[20:21], v[96:97], v[116:117]
	v_pk_fma_f32 v[176:177], v[32:33], v[94:95], v[176:177]
	v_pk_fma_f32 v[116:117], v[22:23], v[92:93], v[116:117]
	v_pk_fma_f32 v[176:177], v[24:25], v[90:91], v[176:177]
	v_pk_fma_f32 v[116:117], v[26:27], v[88:89], v[116:117]
	v_pk_fma_f32 v[176:177], v[34:35], v[86:87], v[176:177]
	v_pk_fma_f32 v[116:117], v[36:37], v[84:85], v[116:117]
	v_pk_fma_f32 v[176:177], v[38:39], v[82:83], v[176:177]
	v_pk_fma_f32 v[116:117], v[40:41], v[80:81], v[116:117]
	v_pk_fma_f32 v[176:177], v[58:59], v[78:79], v[176:177]
	v_pk_fma_f32 v[116:117], v[42:43], v[76:77], v[116:117]
	v_pk_fma_f32 v[176:177], v[44:45], v[74:75], v[176:177]
	v_pk_fma_f32 v[116:117], v[46:47], v[70:71], v[116:117]
	v_pk_fma_f32 v[176:177], v[60:61], v[134:135], v[176:177]
	v_pk_fma_f32 v[116:117], v[48:49], v[130:131], v[116:117]
	v_pk_fma_f32 v[176:177], v[50:51], v[132:133], v[176:177]
	v_pk_fma_f32 v[116:117], v[52:53], v[128:129], v[116:117]
	v_pk_fma_f32 v[176:177], v[62:63], v[126:127], v[176:177]
	v_pk_fma_f32 v[116:117], v[54:55], v[124:125], v[116:117]
	v_pk_fma_f32 v[176:177], v[56:57], v[122:123], v[176:177]
	v_pk_fma_f32 v[116:117], v[64:65], v[120:121], v[116:117]
	s_nop 0
	v_pk_add_f32 v[116:117], v[116:117], v[176:177]
	ds_write_b64 v118, v[116:117]
	v_lshlrev_b32_e32 v118, 16, v167
	s_and_b64 vcc, exec, s[0:1]
	v_and_b32_e32 v119, 0xffff0000, v167
	s_cbranch_vccz .LBB0_1139

.LBB0_1109:
	v_pk_fma_f32 v[112:113], v[4:5], v[112:113], v[66:67]
	v_lshl_add_u32 v114, s45, 11, v139
	v_pk_mul_f32 v[176:177], v[6:7], v[110:111]
	v_add3_u32 v114, v114, v2, s64
	v_pk_fma_f32 v[112:113], v[8:9], v[108:109], v[112:113]
	v_pk_fma_f32 v[176:177], v[28:29], v[106:107], v[176:177]
	v_pk_fma_f32 v[112:113], v[10:11], v[104:105], v[112:113]
	v_pk_fma_f32 v[176:177], v[12:13], v[102:103], v[176:177]
	v_pk_fma_f32 v[112:113], v[14:15], v[100:101], v[112:113]
	v_pk_fma_f32 v[176:177], v[30:31], v[98:99], v[176:177]
	v_pk_fma_f32 v[112:113], v[16:17], v[96:97], v[112:113]
	v_pk_fma_f32 v[176:177], v[18:19], v[94:95], v[176:177]
	v_pk_fma_f32 v[112:113], v[20:21], v[92:93], v[112:113]
	v_pk_fma_f32 v[176:177], v[32:33], v[90:91], v[176:177]
	v_pk_fma_f32 v[112:113], v[22:23], v[88:89], v[112:113]
	v_pk_fma_f32 v[176:177], v[24:25], v[86:87], v[176:177]
	v_pk_fma_f32 v[112:113], v[26:27], v[84:85], v[112:113]
	v_pk_fma_f32 v[176:177], v[34:35], v[82:83], v[176:177]
	v_pk_fma_f32 v[112:113], v[36:37], v[80:81], v[112:113]
	v_pk_fma_f32 v[176:177], v[38:39], v[78:79], v[176:177]
	v_pk_fma_f32 v[112:113], v[40:41], v[76:77], v[112:113]
	v_pk_fma_f32 v[176:177], v[58:59], v[74:75], v[176:177]
	v_pk_fma_f32 v[112:113], v[42:43], v[70:71], v[112:113]
	v_pk_fma_f32 v[176:177], v[44:45], v[134:135], v[176:177]
	v_pk_fma_f32 v[112:113], v[46:47], v[130:131], v[112:113]
	v_pk_fma_f32 v[176:177], v[60:61], v[132:133], v[176:177]
	v_pk_fma_f32 v[112:113], v[48:49], v[128:129], v[112:113]
	v_pk_fma_f32 v[176:177], v[50:51], v[126:127], v[176:177]
	v_pk_fma_f32 v[112:113], v[52:53], v[124:125], v[112:113]
	v_pk_fma_f32 v[176:177], v[62:63], v[122:123], v[176:177]
	v_pk_fma_f32 v[112:113], v[54:55], v[120:121], v[112:113]
	v_pk_fma_f32 v[176:177], v[56:57], v[118:119], v[176:177]
	v_pk_fma_f32 v[112:113], v[64:65], v[116:117], v[112:113]
	s_nop 0
	v_pk_add_f32 v[112:113], v[112:113], v[176:177]
	ds_write_b64 v114, v[112:113]
	v_lshlrev_b32_e32 v114, 16, v165
	s_and_b64 vcc, exec, s[0:1]
	v_and_b32_e32 v115, 0xffff0000, v165
	s_cbranch_vccz .LBB0_1141

.LBB0_1111:
	v_pk_fma_f32 v[108:109], v[4:5], v[108:109], v[66:67]
	v_lshl_add_u32 v110, s42, 11, v139
	v_pk_mul_f32 v[176:177], v[6:7], v[106:107]
	v_add3_u32 v110, v110, v2, s64
	v_pk_fma_f32 v[108:109], v[8:9], v[104:105], v[108:109]
	v_pk_fma_f32 v[176:177], v[28:29], v[102:103], v[176:177]
	v_pk_fma_f32 v[108:109], v[10:11], v[100:101], v[108:109]
	v_pk_fma_f32 v[176:177], v[12:13], v[98:99], v[176:177]
	v_pk_fma_f32 v[108:109], v[14:15], v[96:97], v[108:109]
	v_pk_fma_f32 v[176:177], v[30:31], v[94:95], v[176:177]
	v_pk_fma_f32 v[108:109], v[16:17], v[92:93], v[108:109]
	v_pk_fma_f32 v[176:177], v[18:19], v[90:91], v[176:177]
	v_pk_fma_f32 v[108:109], v[20:21], v[88:89], v[108:109]
	v_pk_fma_f32 v[176:177], v[32:33], v[86:87], v[176:177]
	v_pk_fma_f32 v[108:109], v[22:23], v[84:85], v[108:109]
	v_pk_fma_f32 v[176:177], v[24:25], v[82:83], v[176:177]
	v_pk_fma_f32 v[108:109], v[26:27], v[80:81], v[108:109]
	v_pk_fma_f32 v[176:177], v[34:35], v[78:79], v[176:177]
	v_pk_fma_f32 v[108:109], v[36:37], v[76:77], v[108:109]
	v_pk_fma_f32 v[176:177], v[38:39], v[74:75], v[176:177]
	v_pk_fma_f32 v[108:109], v[40:41], v[70:71], v[108:109]
	v_pk_fma_f32 v[176:177], v[58:59], v[134:135], v[176:177]
	v_pk_fma_f32 v[108:109], v[42:43], v[130:131], v[108:109]
	v_pk_fma_f32 v[176:177], v[44:45], v[132:133], v[176:177]
	v_pk_fma_f32 v[108:109], v[46:47], v[128:129], v[108:109]
	v_pk_fma_f32 v[176:177], v[60:61], v[126:127], v[176:177]
	v_pk_fma_f32 v[108:109], v[48:49], v[124:125], v[108:109]
	v_pk_fma_f32 v[176:177], v[50:51], v[122:123], v[176:177]
	v_pk_fma_f32 v[108:109], v[52:53], v[120:121], v[108:109]
	v_pk_fma_f32 v[176:177], v[62:63], v[118:119], v[176:177]
	v_pk_fma_f32 v[108:109], v[54:55], v[116:117], v[108:109]
	v_pk_fma_f32 v[176:177], v[56:57], v[114:115], v[176:177]
	v_pk_fma_f32 v[108:109], v[64:65], v[112:113], v[108:109]
	s_nop 0
	v_pk_add_f32 v[108:109], v[108:109], v[176:177]
	ds_write_b64 v110, v[108:109]
	v_lshlrev_b32_e32 v110, 16, v163
	s_and_b64 vcc, exec, s[0:1]
	v_and_b32_e32 v111, 0xffff0000, v163
	s_cbranch_vccz .LBB0_1143

.LBB0_1113:
	v_pk_fma_f32 v[104:105], v[4:5], v[104:105], v[66:67]
	v_lshl_add_u32 v106, s40, 11, v139
	v_pk_mul_f32 v[176:177], v[6:7], v[102:103]
	v_add3_u32 v106, v106, v2, s64
	v_pk_fma_f32 v[104:105], v[8:9], v[100:101], v[104:105]
	v_pk_fma_f32 v[176:177], v[28:29], v[98:99], v[176:177]
	v_pk_fma_f32 v[104:105], v[10:11], v[96:97], v[104:105]
	v_pk_fma_f32 v[176:177], v[12:13], v[94:95], v[176:177]
	v_pk_fma_f32 v[104:105], v[14:15], v[92:93], v[104:105]
	v_pk_fma_f32 v[176:177], v[30:31], v[90:91], v[176:177]
	v_pk_fma_f32 v[104:105], v[16:17], v[88:89], v[104:105]
	v_pk_fma_f32 v[176:177], v[18:19], v[86:87], v[176:177]
	v_pk_fma_f32 v[104:105], v[20:21], v[84:85], v[104:105]
	v_pk_fma_f32 v[176:177], v[32:33], v[82:83], v[176:177]
	v_pk_fma_f32 v[104:105], v[22:23], v[80:81], v[104:105]
	v_pk_fma_f32 v[176:177], v[24:25], v[78:79], v[176:177]
	v_pk_fma_f32 v[104:105], v[26:27], v[76:77], v[104:105]
	v_pk_fma_f32 v[176:177], v[34:35], v[74:75], v[176:177]
	v_pk_fma_f32 v[104:105], v[36:37], v[70:71], v[104:105]
	v_pk_fma_f32 v[176:177], v[38:39], v[72:73], v[176:177]
	v_pk_fma_f32 v[104:105], v[40:41], v[130:131], v[104:105]
	v_pk_fma_f32 v[176:177], v[58:59], v[132:133], v[176:177]
	v_pk_fma_f32 v[104:105], v[42:43], v[128:129], v[104:105]
	v_pk_fma_f32 v[176:177], v[44:45], v[126:127], v[176:177]
	v_pk_fma_f32 v[104:105], v[46:47], v[124:125], v[104:105]
	v_pk_fma_f32 v[176:177], v[60:61], v[122:123], v[176:177]
	v_pk_fma_f32 v[104:105], v[48:49], v[120:121], v[104:105]
	v_pk_fma_f32 v[176:177], v[50:51], v[118:119], v[176:177]
	v_pk_fma_f32 v[104:105], v[52:53], v[116:117], v[104:105]
	v_pk_fma_f32 v[176:177], v[62:63], v[114:115], v[176:177]
	v_pk_fma_f32 v[104:105], v[54:55], v[112:113], v[104:105]
	v_pk_fma_f32 v[176:177], v[56:57], v[110:111], v[176:177]
	v_pk_fma_f32 v[104:105], v[64:65], v[108:109], v[104:105]
	s_nop 0
	v_pk_add_f32 v[104:105], v[104:105], v[176:177]
	ds_write_b64 v106, v[104:105]
	v_lshlrev_b32_e32 v106, 16, v161
	s_and_b64 vcc, exec, s[0:1]
	v_and_b32_e32 v107, 0xffff0000, v161
	s_cbranch_vccz .LBB0_1145

.LBB0_1115:
	v_pk_fma_f32 v[100:101], v[4:5], v[100:101], v[66:67]
	v_lshl_add_u32 v102, s38, 11, v139
	v_pk_mul_f32 v[176:177], v[6:7], v[98:99]
	v_add3_u32 v102, v102, v2, s64
	v_pk_fma_f32 v[100:101], v[8:9], v[96:97], v[100:101]
	v_pk_fma_f32 v[176:177], v[28:29], v[94:95], v[176:177]
	v_pk_fma_f32 v[100:101], v[10:11], v[92:93], v[100:101]
	v_pk_fma_f32 v[176:177], v[12:13], v[90:91], v[176:177]
	v_pk_fma_f32 v[100:101], v[14:15], v[88:89], v[100:101]
	v_pk_fma_f32 v[176:177], v[30:31], v[86:87], v[176:177]
	v_pk_fma_f32 v[100:101], v[16:17], v[84:85], v[100:101]
	v_pk_fma_f32 v[176:177], v[18:19], v[82:83], v[176:177]
	v_pk_fma_f32 v[100:101], v[20:21], v[80:81], v[100:101]
	v_pk_fma_f32 v[176:177], v[32:33], v[78:79], v[176:177]
	v_pk_fma_f32 v[100:101], v[22:23], v[76:77], v[100:101]
	v_pk_fma_f32 v[176:177], v[24:25], v[74:75], v[176:177]
	v_pk_fma_f32 v[100:101], v[26:27], v[70:71], v[100:101]
	v_pk_fma_f32 v[176:177], v[34:35], v[72:73], v[176:177]
	v_pk_fma_f32 v[100:101], v[36:37], v[130:131], v[100:101]
	v_pk_fma_f32 v[176:177], v[38:39], v[132:133], v[176:177]
	v_pk_fma_f32 v[100:101], v[40:41], v[128:129], v[100:101]
	v_pk_fma_f32 v[176:177], v[58:59], v[126:127], v[176:177]
	v_pk_fma_f32 v[100:101], v[42:43], v[124:125], v[100:101]
	v_pk_fma_f32 v[176:177], v[44:45], v[122:123], v[176:177]
	v_pk_fma_f32 v[100:101], v[46:47], v[120:121], v[100:101]
	v_pk_fma_f32 v[176:177], v[60:61], v[118:119], v[176:177]
	v_pk_fma_f32 v[100:101], v[48:49], v[116:117], v[100:101]
	v_pk_fma_f32 v[176:177], v[50:51], v[114:115], v[176:177]
	v_pk_fma_f32 v[100:101], v[52:53], v[112:113], v[100:101]
	v_pk_fma_f32 v[176:177], v[62:63], v[110:111], v[176:177]
	v_pk_fma_f32 v[100:101], v[54:55], v[108:109], v[100:101]
	v_pk_fma_f32 v[176:177], v[56:57], v[106:107], v[176:177]
	v_pk_fma_f32 v[100:101], v[64:65], v[104:105], v[100:101]
	s_nop 0
	v_pk_add_f32 v[100:101], v[100:101], v[176:177]
	ds_write_b64 v102, v[100:101]
	v_lshlrev_b32_e32 v102, 16, v159
	s_and_b64 vcc, exec, s[0:1]
	v_and_b32_e32 v103, 0xffff0000, v159
	s_cbranch_vccz .LBB0_1147

.LBB0_1117:
	v_pk_fma_f32 v[96:97], v[4:5], v[96:97], v[66:67]
	v_lshl_add_u32 v98, s36, 11, v139
	v_pk_mul_f32 v[176:177], v[6:7], v[94:95]
	v_add3_u32 v98, v98, v2, s64
	v_pk_fma_f32 v[96:97], v[8:9], v[92:93], v[96:97]
	v_pk_fma_f32 v[176:177], v[28:29], v[90:91], v[176:177]
	v_pk_fma_f32 v[96:97], v[10:11], v[88:89], v[96:97]
	v_pk_fma_f32 v[176:177], v[12:13], v[86:87], v[176:177]
	v_pk_fma_f32 v[96:97], v[14:15], v[84:85], v[96:97]
	v_pk_fma_f32 v[176:177], v[30:31], v[82:83], v[176:177]
	v_pk_fma_f32 v[96:97], v[16:17], v[80:81], v[96:97]
	v_pk_fma_f32 v[176:177], v[18:19], v[78:79], v[176:177]
	v_pk_fma_f32 v[96:97], v[20:21], v[76:77], v[96:97]
	v_pk_fma_f32 v[176:177], v[32:33], v[74:75], v[176:177]
	v_pk_fma_f32 v[96:97], v[22:23], v[70:71], v[96:97]
	v_pk_fma_f32 v[176:177], v[24:25], v[72:73], v[176:177]
	v_pk_fma_f32 v[96:97], v[26:27], v[130:131], v[96:97]
	v_pk_fma_f32 v[176:177], v[34:35], v[132:133], v[176:177]
	v_pk_fma_f32 v[96:97], v[36:37], v[128:129], v[96:97]
	v_pk_fma_f32 v[176:177], v[38:39], v[126:127], v[176:177]
	v_pk_fma_f32 v[96:97], v[40:41], v[124:125], v[96:97]
	v_pk_fma_f32 v[176:177], v[58:59], v[122:123], v[176:177]
	v_pk_fma_f32 v[96:97], v[42:43], v[120:121], v[96:97]
	v_pk_fma_f32 v[176:177], v[44:45], v[118:119], v[176:177]
	v_pk_fma_f32 v[96:97], v[46:47], v[116:117], v[96:97]
	v_pk_fma_f32 v[176:177], v[60:61], v[114:115], v[176:177]
	v_pk_fma_f32 v[96:97], v[48:49], v[112:113], v[96:97]
	v_pk_fma_f32 v[176:177], v[50:51], v[110:111], v[176:177]
	v_pk_fma_f32 v[96:97], v[52:53], v[108:109], v[96:97]
	v_pk_fma_f32 v[176:177], v[62:63], v[106:107], v[176:177]
	v_pk_fma_f32 v[96:97], v[54:55], v[104:105], v[96:97]
	v_pk_fma_f32 v[176:177], v[56:57], v[102:103], v[176:177]
	v_pk_fma_f32 v[96:97], v[64:65], v[100:101], v[96:97]
	s_nop 0
	v_pk_add_f32 v[96:97], v[96:97], v[176:177]
	ds_write_b64 v98, v[96:97]
	v_lshlrev_b32_e32 v98, 16, v157
	s_and_b64 vcc, exec, s[0:1]
	v_and_b32_e32 v99, 0xffff0000, v157
	s_cbranch_vccz .LBB0_1149

.LBB0_1119:
	v_pk_fma_f32 v[92:93], v[4:5], v[92:93], v[66:67]
	v_lshl_add_u32 v94, s34, 11, v139
	v_pk_mul_f32 v[176:177], v[6:7], v[90:91]
	v_add3_u32 v94, v94, v2, s64
	v_pk_fma_f32 v[92:93], v[8:9], v[88:89], v[92:93]
	v_pk_fma_f32 v[176:177], v[28:29], v[86:87], v[176:177]
	v_pk_fma_f32 v[92:93], v[10:11], v[84:85], v[92:93]
	v_pk_fma_f32 v[176:177], v[12:13], v[82:83], v[176:177]
	v_pk_fma_f32 v[92:93], v[14:15], v[80:81], v[92:93]
	v_pk_fma_f32 v[176:177], v[30:31], v[78:79], v[176:177]
	v_pk_fma_f32 v[92:93], v[16:17], v[76:77], v[92:93]
	v_pk_fma_f32 v[176:177], v[18:19], v[74:75], v[176:177]
	v_pk_fma_f32 v[92:93], v[20:21], v[70:71], v[92:93]
	v_pk_fma_f32 v[176:177], v[32:33], v[72:73], v[176:177]
	v_pk_fma_f32 v[92:93], v[22:23], v[130:131], v[92:93]
	v_pk_fma_f32 v[176:177], v[24:25], v[132:133], v[176:177]
	v_pk_fma_f32 v[92:93], v[26:27], v[128:129], v[92:93]
	v_pk_fma_f32 v[176:177], v[34:35], v[126:127], v[176:177]
	v_pk_fma_f32 v[92:93], v[36:37], v[124:125], v[92:93]
	v_pk_fma_f32 v[176:177], v[38:39], v[122:123], v[176:177]
	v_pk_fma_f32 v[92:93], v[40:41], v[120:121], v[92:93]
	v_pk_fma_f32 v[176:177], v[58:59], v[118:119], v[176:177]
	v_pk_fma_f32 v[92:93], v[42:43], v[116:117], v[92:93]
	v_pk_fma_f32 v[176:177], v[44:45], v[114:115], v[176:177]
	v_pk_fma_f32 v[92:93], v[46:47], v[112:113], v[92:93]
	v_pk_fma_f32 v[176:177], v[60:61], v[110:111], v[176:177]
	v_pk_fma_f32 v[92:93], v[48:49], v[108:109], v[92:93]
	v_pk_fma_f32 v[176:177], v[50:51], v[106:107], v[176:177]
	v_pk_fma_f32 v[92:93], v[52:53], v[104:105], v[92:93]
	v_pk_fma_f32 v[176:177], v[62:63], v[102:103], v[176:177]
	v_pk_fma_f32 v[92:93], v[54:55], v[100:101], v[92:93]
	v_pk_fma_f32 v[176:177], v[56:57], v[98:99], v[176:177]
	v_pk_fma_f32 v[92:93], v[64:65], v[96:97], v[92:93]
	s_nop 0
	v_pk_add_f32 v[92:93], v[92:93], v[176:177]
	ds_write_b64 v94, v[92:93]
	v_lshlrev_b32_e32 v94, 16, v155
	s_and_b64 vcc, exec, s[0:1]
	v_and_b32_e32 v95, 0xffff0000, v155
	s_cbranch_vccz .LBB0_1151

.LBB0_1121:
	v_pk_fma_f32 v[88:89], v[4:5], v[88:89], v[66:67]
	v_lshl_add_u32 v90, s31, 11, v139
	v_pk_mul_f32 v[176:177], v[6:7], v[86:87]
	v_add3_u32 v90, v90, v2, s64
	v_pk_fma_f32 v[88:89], v[8:9], v[84:85], v[88:89]
	v_pk_fma_f32 v[176:177], v[28:29], v[82:83], v[176:177]
	v_pk_fma_f32 v[88:89], v[10:11], v[80:81], v[88:89]
	v_pk_fma_f32 v[176:177], v[12:13], v[78:79], v[176:177]
	v_pk_fma_f32 v[88:89], v[14:15], v[76:77], v[88:89]
	v_pk_fma_f32 v[176:177], v[30:31], v[74:75], v[176:177]
	v_pk_fma_f32 v[88:89], v[16:17], v[70:71], v[88:89]
	v_pk_fma_f32 v[176:177], v[18:19], v[72:73], v[176:177]
	v_pk_fma_f32 v[88:89], v[20:21], v[130:131], v[88:89]
	v_pk_fma_f32 v[176:177], v[32:33], v[132:133], v[176:177]
	v_pk_fma_f32 v[88:89], v[22:23], v[128:129], v[88:89]
	v_pk_fma_f32 v[176:177], v[24:25], v[126:127], v[176:177]
	v_pk_fma_f32 v[88:89], v[26:27], v[124:125], v[88:89]
	v_pk_fma_f32 v[176:177], v[34:35], v[122:123], v[176:177]
	v_pk_fma_f32 v[88:89], v[36:37], v[120:121], v[88:89]
	v_pk_fma_f32 v[176:177], v[38:39], v[118:119], v[176:177]
	v_pk_fma_f32 v[88:89], v[40:41], v[116:117], v[88:89]
	v_pk_fma_f32 v[176:177], v[58:59], v[114:115], v[176:177]
	v_pk_fma_f32 v[88:89], v[42:43], v[112:113], v[88:89]
	v_pk_fma_f32 v[176:177], v[44:45], v[110:111], v[176:177]
	v_pk_fma_f32 v[88:89], v[46:47], v[108:109], v[88:89]
	v_pk_fma_f32 v[176:177], v[60:61], v[106:107], v[176:177]
	v_pk_fma_f32 v[88:89], v[48:49], v[104:105], v[88:89]
	v_pk_fma_f32 v[176:177], v[50:51], v[102:103], v[176:177]
	v_pk_fma_f32 v[88:89], v[52:53], v[100:101], v[88:89]
	v_pk_fma_f32 v[176:177], v[62:63], v[98:99], v[176:177]
	v_pk_fma_f32 v[88:89], v[54:55], v[96:97], v[88:89]
	v_pk_fma_f32 v[176:177], v[56:57], v[94:95], v[176:177]
	v_pk_fma_f32 v[88:89], v[64:65], v[92:93], v[88:89]
	s_nop 0
	v_pk_add_f32 v[88:89], v[88:89], v[176:177]
	ds_write_b64 v90, v[88:89]
	v_lshlrev_b32_e32 v90, 16, v153
	s_and_b64 vcc, exec, s[0:1]
	v_and_b32_e32 v91, 0xffff0000, v153
	s_cbranch_vccz .LBB0_1153

.LBB0_1123:
	v_pk_fma_f32 v[84:85], v[4:5], v[84:85], v[66:67]
	v_lshl_add_u32 v86, s29, 11, v139
	v_pk_mul_f32 v[176:177], v[6:7], v[82:83]
	v_add3_u32 v86, v86, v2, s64
	v_pk_fma_f32 v[84:85], v[8:9], v[80:81], v[84:85]
	v_pk_fma_f32 v[176:177], v[28:29], v[78:79], v[176:177]
	v_pk_fma_f32 v[84:85], v[10:11], v[76:77], v[84:85]
	v_pk_fma_f32 v[176:177], v[12:13], v[74:75], v[176:177]
	v_pk_fma_f32 v[84:85], v[14:15], v[70:71], v[84:85]
	v_pk_fma_f32 v[176:177], v[30:31], v[72:73], v[176:177]
	v_pk_fma_f32 v[84:85], v[16:17], v[130:131], v[84:85]
	v_pk_fma_f32 v[176:177], v[18:19], v[132:133], v[176:177]
	v_pk_fma_f32 v[84:85], v[20:21], v[128:129], v[84:85]
	v_pk_fma_f32 v[176:177], v[32:33], v[126:127], v[176:177]
	v_pk_fma_f32 v[84:85], v[22:23], v[124:125], v[84:85]
	v_pk_fma_f32 v[176:177], v[24:25], v[122:123], v[176:177]
	v_pk_fma_f32 v[84:85], v[26:27], v[120:121], v[84:85]
	v_pk_fma_f32 v[176:177], v[34:35], v[118:119], v[176:177]
	v_pk_fma_f32 v[84:85], v[36:37], v[116:117], v[84:85]
	v_pk_fma_f32 v[176:177], v[38:39], v[114:115], v[176:177]
	v_pk_fma_f32 v[84:85], v[40:41], v[112:113], v[84:85]
	v_pk_fma_f32 v[176:177], v[58:59], v[110:111], v[176:177]
	v_pk_fma_f32 v[84:85], v[42:43], v[108:109], v[84:85]
	v_pk_fma_f32 v[176:177], v[44:45], v[106:107], v[176:177]
	v_pk_fma_f32 v[84:85], v[46:47], v[104:105], v[84:85]
	v_pk_fma_f32 v[176:177], v[60:61], v[102:103], v[176:177]
	v_pk_fma_f32 v[84:85], v[48:49], v[100:101], v[84:85]
	v_pk_fma_f32 v[176:177], v[50:51], v[98:99], v[176:177]
	v_pk_fma_f32 v[84:85], v[52:53], v[96:97], v[84:85]
	v_pk_fma_f32 v[176:177], v[62:63], v[94:95], v[176:177]
	v_pk_fma_f32 v[84:85], v[54:55], v[92:93], v[84:85]
	v_pk_fma_f32 v[176:177], v[56:57], v[90:91], v[176:177]
	v_pk_fma_f32 v[84:85], v[64:65], v[88:89], v[84:85]
	s_nop 0
	v_pk_add_f32 v[84:85], v[84:85], v[176:177]
	ds_write_b64 v86, v[84:85]
	v_lshlrev_b32_e32 v86, 16, v151
	s_and_b64 vcc, exec, s[0:1]
	v_and_b32_e32 v87, 0xffff0000, v151
	s_cbranch_vccz .LBB0_1155

.LBB0_1125:
	v_pk_fma_f32 v[80:81], v[4:5], v[80:81], v[66:67]
	v_lshl_add_u32 v82, s27, 11, v139
	v_pk_mul_f32 v[176:177], v[6:7], v[78:79]
	v_add3_u32 v82, v82, v2, s64
	v_pk_fma_f32 v[80:81], v[8:9], v[76:77], v[80:81]
	v_pk_fma_f32 v[176:177], v[28:29], v[74:75], v[176:177]
	v_pk_fma_f32 v[80:81], v[10:11], v[70:71], v[80:81]
	v_pk_fma_f32 v[176:177], v[12:13], v[72:73], v[176:177]
	v_pk_fma_f32 v[80:81], v[14:15], v[130:131], v[80:81]
	v_pk_fma_f32 v[176:177], v[30:31], v[132:133], v[176:177]
	v_pk_fma_f32 v[80:81], v[16:17], v[128:129], v[80:81]
	v_pk_fma_f32 v[176:177], v[18:19], v[126:127], v[176:177]
	v_pk_fma_f32 v[80:81], v[20:21], v[124:125], v[80:81]
	v_pk_fma_f32 v[176:177], v[32:33], v[122:123], v[176:177]
	v_pk_fma_f32 v[80:81], v[22:23], v[120:121], v[80:81]
	v_pk_fma_f32 v[176:177], v[24:25], v[118:119], v[176:177]
	v_pk_fma_f32 v[80:81], v[26:27], v[116:117], v[80:81]
	v_pk_fma_f32 v[176:177], v[34:35], v[114:115], v[176:177]
	v_pk_fma_f32 v[80:81], v[36:37], v[112:113], v[80:81]
	v_pk_fma_f32 v[176:177], v[38:39], v[110:111], v[176:177]
	v_pk_fma_f32 v[80:81], v[40:41], v[108:109], v[80:81]
	v_pk_fma_f32 v[176:177], v[58:59], v[106:107], v[176:177]
	v_pk_fma_f32 v[80:81], v[42:43], v[104:105], v[80:81]
	v_pk_fma_f32 v[176:177], v[44:45], v[102:103], v[176:177]
	v_pk_fma_f32 v[80:81], v[46:47], v[100:101], v[80:81]
	v_pk_fma_f32 v[176:177], v[60:61], v[98:99], v[176:177]
	v_pk_fma_f32 v[80:81], v[48:49], v[96:97], v[80:81]
	v_pk_fma_f32 v[176:177], v[50:51], v[94:95], v[176:177]
	v_pk_fma_f32 v[80:81], v[52:53], v[92:93], v[80:81]
	v_pk_fma_f32 v[176:177], v[62:63], v[90:91], v[176:177]
	v_pk_fma_f32 v[80:81], v[54:55], v[88:89], v[80:81]
	v_pk_fma_f32 v[176:177], v[56:57], v[86:87], v[176:177]
	v_pk_fma_f32 v[80:81], v[64:65], v[84:85], v[80:81]
	s_nop 0
	v_pk_add_f32 v[80:81], v[80:81], v[176:177]
	ds_write_b64 v82, v[80:81]
	v_lshlrev_b32_e32 v82, 16, v149
	s_and_b64 vcc, exec, s[0:1]
	v_and_b32_e32 v83, 0xffff0000, v149
	s_cbranch_vccz .LBB0_1157

.LBB0_1127:
	v_pk_fma_f32 v[76:77], v[4:5], v[76:77], v[66:67]
	v_lshl_add_u32 v78, s25, 11, v139
	v_pk_mul_f32 v[176:177], v[6:7], v[74:75]
	v_add3_u32 v78, v78, v2, s64
	v_pk_fma_f32 v[76:77], v[8:9], v[70:71], v[76:77]
	v_pk_fma_f32 v[176:177], v[28:29], v[72:73], v[176:177]
	v_pk_fma_f32 v[76:77], v[10:11], v[130:131], v[76:77]
	v_pk_fma_f32 v[176:177], v[12:13], v[132:133], v[176:177]
	v_pk_fma_f32 v[76:77], v[14:15], v[128:129], v[76:77]
	v_pk_fma_f32 v[176:177], v[30:31], v[126:127], v[176:177]
	v_pk_fma_f32 v[76:77], v[16:17], v[124:125], v[76:77]
	v_pk_fma_f32 v[176:177], v[18:19], v[122:123], v[176:177]
	v_pk_fma_f32 v[76:77], v[20:21], v[120:121], v[76:77]
	v_pk_fma_f32 v[176:177], v[32:33], v[118:119], v[176:177]
	v_pk_fma_f32 v[76:77], v[22:23], v[116:117], v[76:77]
	v_pk_fma_f32 v[176:177], v[24:25], v[114:115], v[176:177]
	v_pk_fma_f32 v[76:77], v[26:27], v[112:113], v[76:77]
	v_pk_fma_f32 v[176:177], v[34:35], v[110:111], v[176:177]
	v_pk_fma_f32 v[76:77], v[36:37], v[108:109], v[76:77]
	v_pk_fma_f32 v[176:177], v[38:39], v[106:107], v[176:177]
	v_pk_fma_f32 v[76:77], v[40:41], v[104:105], v[76:77]
	v_pk_fma_f32 v[176:177], v[58:59], v[102:103], v[176:177]
	v_pk_fma_f32 v[76:77], v[42:43], v[100:101], v[76:77]
	v_pk_fma_f32 v[176:177], v[44:45], v[98:99], v[176:177]
	v_pk_fma_f32 v[76:77], v[46:47], v[96:97], v[76:77]
	v_pk_fma_f32 v[176:177], v[60:61], v[94:95], v[176:177]
	v_pk_fma_f32 v[76:77], v[48:49], v[92:93], v[76:77]
	v_pk_fma_f32 v[176:177], v[50:51], v[90:91], v[176:177]
	v_pk_fma_f32 v[76:77], v[52:53], v[88:89], v[76:77]
	v_pk_fma_f32 v[176:177], v[62:63], v[86:87], v[176:177]
	v_pk_fma_f32 v[76:77], v[54:55], v[84:85], v[76:77]
	v_pk_fma_f32 v[176:177], v[56:57], v[82:83], v[176:177]
	v_pk_fma_f32 v[76:77], v[64:65], v[80:81], v[76:77]
	s_nop 0
	v_pk_add_f32 v[76:77], v[76:77], v[176:177]
	ds_write_b64 v78, v[76:77]
	v_lshlrev_b32_e32 v78, 16, v145
	s_and_b64 vcc, exec, s[0:1]
	v_and_b32_e32 v79, 0xffff0000, v145
	s_cbranch_vccz .LBB0_1159

.LBB0_1129:
	v_pk_fma_f32 v[70:71], v[4:5], v[70:71], v[66:67]
	v_lshl_add_u32 v74, s23, 11, v139
	v_pk_mul_f32 v[176:177], v[6:7], v[72:73]
	v_add3_u32 v74, v74, v2, s64
	v_pk_fma_f32 v[70:71], v[8:9], v[130:131], v[70:71]
	v_pk_fma_f32 v[176:177], v[28:29], v[132:133], v[176:177]
	v_pk_fma_f32 v[70:71], v[10:11], v[128:129], v[70:71]
	v_pk_fma_f32 v[176:177], v[12:13], v[126:127], v[176:177]
	v_pk_fma_f32 v[70:71], v[14:15], v[124:125], v[70:71]
	v_pk_fma_f32 v[176:177], v[30:31], v[122:123], v[176:177]
	v_pk_fma_f32 v[70:71], v[16:17], v[120:121], v[70:71]
	v_pk_fma_f32 v[176:177], v[18:19], v[118:119], v[176:177]
	v_pk_fma_f32 v[70:71], v[20:21], v[116:117], v[70:71]
	v_pk_fma_f32 v[176:177], v[32:33], v[114:115], v[176:177]
	v_pk_fma_f32 v[70:71], v[22:23], v[112:113], v[70:71]
	v_pk_fma_f32 v[176:177], v[24:25], v[110:111], v[176:177]
	v_pk_fma_f32 v[70:71], v[26:27], v[108:109], v[70:71]
	v_pk_fma_f32 v[176:177], v[34:35], v[106:107], v[176:177]
	v_pk_fma_f32 v[70:71], v[36:37], v[104:105], v[70:71]
	v_pk_fma_f32 v[176:177], v[38:39], v[102:103], v[176:177]
	v_pk_fma_f32 v[70:71], v[40:41], v[100:101], v[70:71]
	v_pk_fma_f32 v[176:177], v[58:59], v[98:99], v[176:177]
	v_pk_fma_f32 v[70:71], v[42:43], v[96:97], v[70:71]
	v_pk_fma_f32 v[176:177], v[44:45], v[94:95], v[176:177]
	v_pk_fma_f32 v[70:71], v[46:47], v[92:93], v[70:71]
	v_pk_fma_f32 v[176:177], v[60:61], v[90:91], v[176:177]
	v_pk_fma_f32 v[70:71], v[48:49], v[88:89], v[70:71]
	v_pk_fma_f32 v[176:177], v[50:51], v[86:87], v[176:177]
	v_pk_fma_f32 v[70:71], v[52:53], v[84:85], v[70:71]
	v_pk_fma_f32 v[176:177], v[62:63], v[82:83], v[176:177]
	v_pk_fma_f32 v[70:71], v[54:55], v[80:81], v[70:71]
	v_pk_fma_f32 v[176:177], v[56:57], v[78:79], v[176:177]
	v_pk_fma_f32 v[70:71], v[64:65], v[76:77], v[70:71]
	s_nop 0
	v_pk_add_f32 v[70:71], v[70:71], v[176:177]
	ds_write_b64 v74, v[70:71]
	v_lshlrev_b32_e32 v74, 16, v143
	s_andn2_b64 vcc, exec, s[16:17]
	v_and_b32_e32 v75, 0xffff0000, v143
	s_cbranch_vccz .LBB0_1161

.LBB0_1131:
	v_pk_fma_f32 v[72:73], v[4:5], v[130:131], v[66:67]
	v_pk_mul_f32 v[176:177], v[6:7], v[132:133]
	v_pk_fma_f32 v[72:73], v[8:9], v[128:129], v[72:73]
	v_pk_fma_f32 v[176:177], v[28:29], v[126:127], v[176:177]
	v_pk_fma_f32 v[72:73], v[10:11], v[124:125], v[72:73]
	v_pk_fma_f32 v[176:177], v[12:13], v[122:123], v[176:177]
	v_pk_fma_f32 v[72:73], v[14:15], v[120:121], v[72:73]
	v_pk_fma_f32 v[176:177], v[30:31], v[118:119], v[176:177]
	v_pk_fma_f32 v[72:73], v[16:17], v[116:117], v[72:73]
	v_pk_fma_f32 v[176:177], v[18:19], v[114:115], v[176:177]
	v_pk_fma_f32 v[72:73], v[20:21], v[112:113], v[72:73]
	v_pk_fma_f32 v[176:177], v[32:33], v[110:111], v[176:177]
	v_pk_fma_f32 v[72:73], v[22:23], v[108:109], v[72:73]
	v_pk_fma_f32 v[176:177], v[24:25], v[106:107], v[176:177]
	v_pk_fma_f32 v[72:73], v[26:27], v[104:105], v[72:73]
	v_pk_fma_f32 v[176:177], v[34:35], v[102:103], v[176:177]
	v_pk_fma_f32 v[72:73], v[36:37], v[100:101], v[72:73]
	v_pk_fma_f32 v[176:177], v[38:39], v[98:99], v[176:177]
	v_pk_fma_f32 v[72:73], v[40:41], v[96:97], v[72:73]
	v_pk_fma_f32 v[176:177], v[58:59], v[94:95], v[176:177]
	v_pk_fma_f32 v[72:73], v[42:43], v[92:93], v[72:73]
	v_pk_fma_f32 v[176:177], v[44:45], v[90:91], v[176:177]
	v_pk_fma_f32 v[72:73], v[46:47], v[88:89], v[72:73]
	v_pk_fma_f32 v[176:177], v[60:61], v[86:87], v[176:177]
	v_pk_fma_f32 v[72:73], v[48:49], v[84:85], v[72:73]
	v_pk_fma_f32 v[176:177], v[50:51], v[82:83], v[176:177]
	v_pk_fma_f32 v[72:73], v[52:53], v[80:81], v[72:73]
	v_pk_fma_f32 v[176:177], v[62:63], v[78:79], v[176:177]
	v_pk_fma_f32 v[72:73], v[54:55], v[76:77], v[72:73]
	v_pk_fma_f32 v[176:177], v[56:57], v[74:75], v[176:177]
	v_pk_fma_f32 v[72:73], v[64:65], v[70:71], v[72:73]
	s_nop 0
	v_pk_add_f32 v[72:73], v[72:73], v[176:177]
	ds_write_b64 v140, v[72:73]
	v_lshlrev_b32_e32 v72, 16, v142
	s_andn2_b64 vcc, exec, s[20:21]
	v_and_b32_e32 v73, 0xffff0000, v142
	s_cbranch_vccnz .LBB0_1035
	s_branch .LBB0_1163

.LBB0_1133:
	v_pk_fma_f32 v[126:127], v[4:5], v[126:127], v[66:67]
	v_lshl_add_u32 v128, s52, 11, v139
	v_pk_mul_f32 v[176:177], v[6:7], v[124:125]
	v_add3_u32 v128, v128, v2, s64
	v_pk_fma_f32 v[126:127], v[8:9], v[122:123], v[126:127]
	v_pk_fma_f32 v[176:177], v[28:29], v[120:121], v[176:177]
	v_pk_fma_f32 v[126:127], v[10:11], v[118:119], v[126:127]
	v_pk_fma_f32 v[176:177], v[12:13], v[116:117], v[176:177]
	v_pk_fma_f32 v[126:127], v[14:15], v[114:115], v[126:127]
	v_pk_fma_f32 v[176:177], v[30:31], v[112:113], v[176:177]
	v_pk_fma_f32 v[126:127], v[16:17], v[110:111], v[126:127]
	v_pk_fma_f32 v[176:177], v[18:19], v[108:109], v[176:177]
	v_pk_fma_f32 v[126:127], v[20:21], v[106:107], v[126:127]
	v_pk_fma_f32 v[176:177], v[32:33], v[104:105], v[176:177]
	v_pk_fma_f32 v[126:127], v[22:23], v[102:103], v[126:127]
	v_pk_fma_f32 v[176:177], v[24:25], v[100:101], v[176:177]
	v_pk_fma_f32 v[126:127], v[26:27], v[98:99], v[126:127]
	v_pk_fma_f32 v[176:177], v[34:35], v[96:97], v[176:177]
	v_pk_fma_f32 v[126:127], v[36:37], v[94:95], v[126:127]
	v_pk_fma_f32 v[176:177], v[38:39], v[92:93], v[176:177]
	v_pk_fma_f32 v[126:127], v[40:41], v[90:91], v[126:127]
	v_pk_fma_f32 v[176:177], v[58:59], v[88:89], v[176:177]
	v_pk_fma_f32 v[126:127], v[42:43], v[86:87], v[126:127]
	v_pk_fma_f32 v[176:177], v[44:45], v[84:85], v[176:177]
	v_pk_fma_f32 v[126:127], v[46:47], v[82:83], v[126:127]
	v_pk_fma_f32 v[176:177], v[60:61], v[80:81], v[176:177]
	v_pk_fma_f32 v[126:127], v[48:49], v[78:79], v[126:127]
	v_pk_fma_f32 v[176:177], v[50:51], v[76:77], v[176:177]
	v_pk_fma_f32 v[126:127], v[52:53], v[74:75], v[126:127]
	v_pk_fma_f32 v[176:177], v[62:63], v[70:71], v[176:177]
	v_pk_fma_f32 v[126:127], v[54:55], v[134:135], v[126:127]
	v_pk_fma_f32 v[176:177], v[56:57], v[130:131], v[176:177]
	v_pk_fma_f32 v[126:127], v[64:65], v[132:133], v[126:127]
	s_nop 0
	v_pk_add_f32 v[126:127], v[126:127], v[176:177]
	ds_write_b64 v128, v[126:127]
	v_lshlrev_b32_e32 v128, 16, v172
	s_and_b64 vcc, exec, s[0:1]
	v_and_b32_e32 v129, 0xffff0000, v172
	s_cbranch_vccz .LBB0_1103

.LBB0_1135:
	v_pk_fma_f32 v[122:123], v[4:5], v[122:123], v[66:67]
	v_lshl_add_u32 v124, s50, 11, v139
	v_pk_mul_f32 v[176:177], v[6:7], v[120:121]
	v_add3_u32 v124, v124, v2, s64
	v_pk_fma_f32 v[122:123], v[8:9], v[118:119], v[122:123]
	v_pk_fma_f32 v[176:177], v[28:29], v[116:117], v[176:177]
	v_pk_fma_f32 v[122:123], v[10:11], v[114:115], v[122:123]
	v_pk_fma_f32 v[176:177], v[12:13], v[112:113], v[176:177]
	v_pk_fma_f32 v[122:123], v[14:15], v[110:111], v[122:123]
	v_pk_fma_f32 v[176:177], v[30:31], v[108:109], v[176:177]
	v_pk_fma_f32 v[122:123], v[16:17], v[106:107], v[122:123]
	v_pk_fma_f32 v[176:177], v[18:19], v[104:105], v[176:177]
	v_pk_fma_f32 v[122:123], v[20:21], v[102:103], v[122:123]
	v_pk_fma_f32 v[176:177], v[32:33], v[100:101], v[176:177]
	v_pk_fma_f32 v[122:123], v[22:23], v[98:99], v[122:123]
	v_pk_fma_f32 v[176:177], v[24:25], v[96:97], v[176:177]
	v_pk_fma_f32 v[122:123], v[26:27], v[94:95], v[122:123]
	v_pk_fma_f32 v[176:177], v[34:35], v[92:93], v[176:177]
	v_pk_fma_f32 v[122:123], v[36:37], v[90:91], v[122:123]
	v_pk_fma_f32 v[176:177], v[38:39], v[88:89], v[176:177]
	v_pk_fma_f32 v[122:123], v[40:41], v[86:87], v[122:123]
	v_pk_fma_f32 v[176:177], v[58:59], v[84:85], v[176:177]
	v_pk_fma_f32 v[122:123], v[42:43], v[82:83], v[122:123]
	v_pk_fma_f32 v[176:177], v[44:45], v[80:81], v[176:177]
	v_pk_fma_f32 v[122:123], v[46:47], v[78:79], v[122:123]
	v_pk_fma_f32 v[176:177], v[60:61], v[76:77], v[176:177]
	v_pk_fma_f32 v[122:123], v[48:49], v[74:75], v[122:123]
	v_pk_fma_f32 v[176:177], v[50:51], v[70:71], v[176:177]
	v_pk_fma_f32 v[122:123], v[52:53], v[134:135], v[122:123]
	v_pk_fma_f32 v[176:177], v[62:63], v[130:131], v[176:177]
	v_pk_fma_f32 v[122:123], v[54:55], v[132:133], v[122:123]
	v_pk_fma_f32 v[176:177], v[56:57], v[128:129], v[176:177]
	v_pk_fma_f32 v[122:123], v[64:65], v[126:127], v[122:123]
	s_nop 0
	v_pk_add_f32 v[122:123], v[122:123], v[176:177]
	ds_write_b64 v124, v[122:123]
	v_lshlrev_b32_e32 v124, 16, v170
	s_and_b64 vcc, exec, s[0:1]
	v_and_b32_e32 v125, 0xffff0000, v170
	s_cbranch_vccz .LBB0_1105

.LBB0_1137:
	v_pk_fma_f32 v[118:119], v[4:5], v[118:119], v[66:67]
	v_lshl_add_u32 v120, s48, 11, v139
	v_pk_mul_f32 v[176:177], v[6:7], v[116:117]
	v_add3_u32 v120, v120, v2, s64
	v_pk_fma_f32 v[118:119], v[8:9], v[114:115], v[118:119]
	v_pk_fma_f32 v[176:177], v[28:29], v[112:113], v[176:177]
	v_pk_fma_f32 v[118:119], v[10:11], v[110:111], v[118:119]
	v_pk_fma_f32 v[176:177], v[12:13], v[108:109], v[176:177]
	v_pk_fma_f32 v[118:119], v[14:15], v[106:107], v[118:119]
	v_pk_fma_f32 v[176:177], v[30:31], v[104:105], v[176:177]
	v_pk_fma_f32 v[118:119], v[16:17], v[102:103], v[118:119]
	v_pk_fma_f32 v[176:177], v[18:19], v[100:101], v[176:177]
	v_pk_fma_f32 v[118:119], v[20:21], v[98:99], v[118:119]
	v_pk_fma_f32 v[176:177], v[32:33], v[96:97], v[176:177]
	v_pk_fma_f32 v[118:119], v[22:23], v[94:95], v[118:119]
	v_pk_fma_f32 v[176:177], v[24:25], v[92:93], v[176:177]
	v_pk_fma_f32 v[118:119], v[26:27], v[90:91], v[118:119]
	v_pk_fma_f32 v[176:177], v[34:35], v[88:89], v[176:177]
	v_pk_fma_f32 v[118:119], v[36:37], v[86:87], v[118:119]
	v_pk_fma_f32 v[176:177], v[38:39], v[84:85], v[176:177]
	v_pk_fma_f32 v[118:119], v[40:41], v[82:83], v[118:119]
	v_pk_fma_f32 v[176:177], v[58:59], v[80:81], v[176:177]
	v_pk_fma_f32 v[118:119], v[42:43], v[78:79], v[118:119]
	v_pk_fma_f32 v[176:177], v[44:45], v[76:77], v[176:177]
	v_pk_fma_f32 v[118:119], v[46:47], v[74:75], v[118:119]
	v_pk_fma_f32 v[176:177], v[60:61], v[70:71], v[176:177]
	v_pk_fma_f32 v[118:119], v[48:49], v[134:135], v[118:119]
	v_pk_fma_f32 v[176:177], v[50:51], v[130:131], v[176:177]
	v_pk_fma_f32 v[118:119], v[52:53], v[132:133], v[118:119]
	v_pk_fma_f32 v[176:177], v[62:63], v[128:129], v[176:177]
	v_pk_fma_f32 v[118:119], v[54:55], v[126:127], v[118:119]
	v_pk_fma_f32 v[176:177], v[56:57], v[124:125], v[176:177]
	v_pk_fma_f32 v[118:119], v[64:65], v[122:123], v[118:119]
	s_nop 0
	v_pk_add_f32 v[118:119], v[118:119], v[176:177]
	ds_write_b64 v120, v[118:119]
	v_lshlrev_b32_e32 v120, 16, v168
	s_and_b64 vcc, exec, s[0:1]
	v_and_b32_e32 v121, 0xffff0000, v168
	s_cbranch_vccz .LBB0_1107

.LBB0_1139:
	v_pk_fma_f32 v[114:115], v[4:5], v[114:115], v[66:67]
	v_lshl_add_u32 v116, s46, 11, v139
	v_pk_mul_f32 v[176:177], v[6:7], v[112:113]
	v_add3_u32 v116, v116, v2, s64
	v_pk_fma_f32 v[114:115], v[8:9], v[110:111], v[114:115]
	v_pk_fma_f32 v[176:177], v[28:29], v[108:109], v[176:177]
	v_pk_fma_f32 v[114:115], v[10:11], v[106:107], v[114:115]
	v_pk_fma_f32 v[176:177], v[12:13], v[104:105], v[176:177]
	v_pk_fma_f32 v[114:115], v[14:15], v[102:103], v[114:115]
	v_pk_fma_f32 v[176:177], v[30:31], v[100:101], v[176:177]
	v_pk_fma_f32 v[114:115], v[16:17], v[98:99], v[114:115]
	v_pk_fma_f32 v[176:177], v[18:19], v[96:97], v[176:177]
	v_pk_fma_f32 v[114:115], v[20:21], v[94:95], v[114:115]
	v_pk_fma_f32 v[176:177], v[32:33], v[92:93], v[176:177]
	v_pk_fma_f32 v[114:115], v[22:23], v[90:91], v[114:115]
	v_pk_fma_f32 v[176:177], v[24:25], v[88:89], v[176:177]
	v_pk_fma_f32 v[114:115], v[26:27], v[86:87], v[114:115]
	v_pk_fma_f32 v[176:177], v[34:35], v[84:85], v[176:177]
	v_pk_fma_f32 v[114:115], v[36:37], v[82:83], v[114:115]
	v_pk_fma_f32 v[176:177], v[38:39], v[80:81], v[176:177]
	v_pk_fma_f32 v[114:115], v[40:41], v[78:79], v[114:115]
	v_pk_fma_f32 v[176:177], v[58:59], v[76:77], v[176:177]
	v_pk_fma_f32 v[114:115], v[42:43], v[74:75], v[114:115]
	v_pk_fma_f32 v[176:177], v[44:45], v[70:71], v[176:177]
	v_pk_fma_f32 v[114:115], v[46:47], v[134:135], v[114:115]
	v_pk_fma_f32 v[176:177], v[60:61], v[130:131], v[176:177]
	v_pk_fma_f32 v[114:115], v[48:49], v[132:133], v[114:115]
	v_pk_fma_f32 v[176:177], v[50:51], v[128:129], v[176:177]
	v_pk_fma_f32 v[114:115], v[52:53], v[126:127], v[114:115]
	v_pk_fma_f32 v[176:177], v[62:63], v[124:125], v[176:177]
	v_pk_fma_f32 v[114:115], v[54:55], v[122:123], v[114:115]
	v_pk_fma_f32 v[176:177], v[56:57], v[120:121], v[176:177]
	v_pk_fma_f32 v[114:115], v[64:65], v[118:119], v[114:115]
	s_nop 0
	v_pk_add_f32 v[114:115], v[114:115], v[176:177]
	ds_write_b64 v116, v[114:115]
	v_lshlrev_b32_e32 v116, 16, v166
	s_and_b64 vcc, exec, s[0:1]
	v_and_b32_e32 v117, 0xffff0000, v166
	s_cbranch_vccz .LBB0_1109

.LBB0_1141:
	v_pk_fma_f32 v[110:111], v[4:5], v[110:111], v[66:67]
	v_lshl_add_u32 v112, s44, 11, v139
	v_pk_mul_f32 v[176:177], v[6:7], v[108:109]
	v_add3_u32 v112, v112, v2, s64
	v_pk_fma_f32 v[110:111], v[8:9], v[106:107], v[110:111]
	v_pk_fma_f32 v[176:177], v[28:29], v[104:105], v[176:177]
	v_pk_fma_f32 v[110:111], v[10:11], v[102:103], v[110:111]
	v_pk_fma_f32 v[176:177], v[12:13], v[100:101], v[176:177]
	v_pk_fma_f32 v[110:111], v[14:15], v[98:99], v[110:111]
	v_pk_fma_f32 v[176:177], v[30:31], v[96:97], v[176:177]
	v_pk_fma_f32 v[110:111], v[16:17], v[94:95], v[110:111]
	v_pk_fma_f32 v[176:177], v[18:19], v[92:93], v[176:177]
	v_pk_fma_f32 v[110:111], v[20:21], v[90:91], v[110:111]
	v_pk_fma_f32 v[176:177], v[32:33], v[88:89], v[176:177]
	v_pk_fma_f32 v[110:111], v[22:23], v[86:87], v[110:111]
	v_pk_fma_f32 v[176:177], v[24:25], v[84:85], v[176:177]
	v_pk_fma_f32 v[110:111], v[26:27], v[82:83], v[110:111]
	v_pk_fma_f32 v[176:177], v[34:35], v[80:81], v[176:177]
	v_pk_fma_f32 v[110:111], v[36:37], v[78:79], v[110:111]
	v_pk_fma_f32 v[176:177], v[38:39], v[76:77], v[176:177]
	v_pk_fma_f32 v[110:111], v[40:41], v[74:75], v[110:111]
	v_pk_fma_f32 v[176:177], v[58:59], v[70:71], v[176:177]
	v_pk_fma_f32 v[110:111], v[42:43], v[134:135], v[110:111]
	v_pk_fma_f32 v[176:177], v[44:45], v[130:131], v[176:177]
	v_pk_fma_f32 v[110:111], v[46:47], v[132:133], v[110:111]
	v_pk_fma_f32 v[176:177], v[60:61], v[128:129], v[176:177]
	v_pk_fma_f32 v[110:111], v[48:49], v[126:127], v[110:111]
	v_pk_fma_f32 v[176:177], v[50:51], v[124:125], v[176:177]
	v_pk_fma_f32 v[110:111], v[52:53], v[122:123], v[110:111]
	v_pk_fma_f32 v[176:177], v[62:63], v[120:121], v[176:177]
	v_pk_fma_f32 v[110:111], v[54:55], v[118:119], v[110:111]
	v_pk_fma_f32 v[176:177], v[56:57], v[116:117], v[176:177]
	v_pk_fma_f32 v[110:111], v[64:65], v[114:115], v[110:111]
	s_nop 0
	v_pk_add_f32 v[110:111], v[110:111], v[176:177]
	ds_write_b64 v112, v[110:111]
	v_lshlrev_b32_e32 v112, 16, v164
	s_and_b64 vcc, exec, s[0:1]
	v_and_b32_e32 v113, 0xffff0000, v164
	s_cbranch_vccz .LBB0_1111

.LBB0_1143:
	v_pk_fma_f32 v[106:107], v[4:5], v[106:107], v[66:67]
	v_lshl_add_u32 v108, s41, 11, v139
	v_pk_mul_f32 v[176:177], v[6:7], v[104:105]
	v_add3_u32 v108, v108, v2, s64
	v_pk_fma_f32 v[106:107], v[8:9], v[102:103], v[106:107]
	v_pk_fma_f32 v[176:177], v[28:29], v[100:101], v[176:177]
	v_pk_fma_f32 v[106:107], v[10:11], v[98:99], v[106:107]
	v_pk_fma_f32 v[176:177], v[12:13], v[96:97], v[176:177]
	v_pk_fma_f32 v[106:107], v[14:15], v[94:95], v[106:107]
	v_pk_fma_f32 v[176:177], v[30:31], v[92:93], v[176:177]
	v_pk_fma_f32 v[106:107], v[16:17], v[90:91], v[106:107]
	v_pk_fma_f32 v[176:177], v[18:19], v[88:89], v[176:177]
	v_pk_fma_f32 v[106:107], v[20:21], v[86:87], v[106:107]
	v_pk_fma_f32 v[176:177], v[32:33], v[84:85], v[176:177]
	v_pk_fma_f32 v[106:107], v[22:23], v[82:83], v[106:107]
	v_pk_fma_f32 v[176:177], v[24:25], v[80:81], v[176:177]
	v_pk_fma_f32 v[106:107], v[26:27], v[78:79], v[106:107]
	v_pk_fma_f32 v[176:177], v[34:35], v[76:77], v[176:177]
	v_pk_fma_f32 v[106:107], v[36:37], v[74:75], v[106:107]
	v_pk_fma_f32 v[176:177], v[38:39], v[70:71], v[176:177]
	v_pk_fma_f32 v[106:107], v[40:41], v[72:73], v[106:107]
	v_pk_fma_f32 v[176:177], v[58:59], v[130:131], v[176:177]
	v_pk_fma_f32 v[106:107], v[42:43], v[132:133], v[106:107]
	v_pk_fma_f32 v[176:177], v[44:45], v[128:129], v[176:177]
	v_pk_fma_f32 v[106:107], v[46:47], v[126:127], v[106:107]
	v_pk_fma_f32 v[176:177], v[60:61], v[124:125], v[176:177]
	v_pk_fma_f32 v[106:107], v[48:49], v[122:123], v[106:107]
	v_pk_fma_f32 v[176:177], v[50:51], v[120:121], v[176:177]
	v_pk_fma_f32 v[106:107], v[52:53], v[118:119], v[106:107]
	v_pk_fma_f32 v[176:177], v[62:63], v[116:117], v[176:177]
	v_pk_fma_f32 v[106:107], v[54:55], v[114:115], v[106:107]
	v_pk_fma_f32 v[176:177], v[56:57], v[112:113], v[176:177]
	v_pk_fma_f32 v[106:107], v[64:65], v[110:111], v[106:107]
	s_nop 0
	v_pk_add_f32 v[106:107], v[106:107], v[176:177]
	ds_write_b64 v108, v[106:107]
	v_lshlrev_b32_e32 v108, 16, v162
	s_and_b64 vcc, exec, s[0:1]
	v_and_b32_e32 v109, 0xffff0000, v162
	s_cbranch_vccz .LBB0_1113

.LBB0_1145:
	v_pk_fma_f32 v[102:103], v[4:5], v[102:103], v[66:67]
	v_lshl_add_u32 v104, s39, 11, v139
	v_pk_mul_f32 v[176:177], v[6:7], v[100:101]
	v_add3_u32 v104, v104, v2, s64
	v_pk_fma_f32 v[102:103], v[8:9], v[98:99], v[102:103]
	v_pk_fma_f32 v[176:177], v[28:29], v[96:97], v[176:177]
	v_pk_fma_f32 v[102:103], v[10:11], v[94:95], v[102:103]
	v_pk_fma_f32 v[176:177], v[12:13], v[92:93], v[176:177]
	v_pk_fma_f32 v[102:103], v[14:15], v[90:91], v[102:103]
	v_pk_fma_f32 v[176:177], v[30:31], v[88:89], v[176:177]
	v_pk_fma_f32 v[102:103], v[16:17], v[86:87], v[102:103]
	v_pk_fma_f32 v[176:177], v[18:19], v[84:85], v[176:177]
	v_pk_fma_f32 v[102:103], v[20:21], v[82:83], v[102:103]
	v_pk_fma_f32 v[176:177], v[32:33], v[80:81], v[176:177]
	v_pk_fma_f32 v[102:103], v[22:23], v[78:79], v[102:103]
	v_pk_fma_f32 v[176:177], v[24:25], v[76:77], v[176:177]
	v_pk_fma_f32 v[102:103], v[26:27], v[74:75], v[102:103]
	v_pk_fma_f32 v[176:177], v[34:35], v[70:71], v[176:177]
	v_pk_fma_f32 v[102:103], v[36:37], v[72:73], v[102:103]
	v_pk_fma_f32 v[176:177], v[38:39], v[130:131], v[176:177]
	v_pk_fma_f32 v[102:103], v[40:41], v[132:133], v[102:103]
	v_pk_fma_f32 v[176:177], v[58:59], v[128:129], v[176:177]
	v_pk_fma_f32 v[102:103], v[42:43], v[126:127], v[102:103]
	v_pk_fma_f32 v[176:177], v[44:45], v[124:125], v[176:177]
	v_pk_fma_f32 v[102:103], v[46:47], v[122:123], v[102:103]
	v_pk_fma_f32 v[176:177], v[60:61], v[120:121], v[176:177]
	v_pk_fma_f32 v[102:103], v[48:49], v[118:119], v[102:103]
	v_pk_fma_f32 v[176:177], v[50:51], v[116:117], v[176:177]
	v_pk_fma_f32 v[102:103], v[52:53], v[114:115], v[102:103]
	v_pk_fma_f32 v[176:177], v[62:63], v[112:113], v[176:177]
	v_pk_fma_f32 v[102:103], v[54:55], v[110:111], v[102:103]
	v_pk_fma_f32 v[176:177], v[56:57], v[108:109], v[176:177]
	v_pk_fma_f32 v[102:103], v[64:65], v[106:107], v[102:103]
	s_nop 0
	v_pk_add_f32 v[102:103], v[102:103], v[176:177]
	ds_write_b64 v104, v[102:103]
	v_lshlrev_b32_e32 v104, 16, v160
	s_and_b64 vcc, exec, s[0:1]
	v_and_b32_e32 v105, 0xffff0000, v160
	s_cbranch_vccz .LBB0_1115

.LBB0_1147:
	v_pk_fma_f32 v[98:99], v[4:5], v[98:99], v[66:67]
	v_lshl_add_u32 v100, s37, 11, v139
	v_pk_mul_f32 v[176:177], v[6:7], v[96:97]
	v_add3_u32 v100, v100, v2, s64
	v_pk_fma_f32 v[98:99], v[8:9], v[94:95], v[98:99]
	v_pk_fma_f32 v[176:177], v[28:29], v[92:93], v[176:177]
	v_pk_fma_f32 v[98:99], v[10:11], v[90:91], v[98:99]
	v_pk_fma_f32 v[176:177], v[12:13], v[88:89], v[176:177]
	v_pk_fma_f32 v[98:99], v[14:15], v[86:87], v[98:99]
	v_pk_fma_f32 v[176:177], v[30:31], v[84:85], v[176:177]
	v_pk_fma_f32 v[98:99], v[16:17], v[82:83], v[98:99]
	v_pk_fma_f32 v[176:177], v[18:19], v[80:81], v[176:177]
	v_pk_fma_f32 v[98:99], v[20:21], v[78:79], v[98:99]
	v_pk_fma_f32 v[176:177], v[32:33], v[76:77], v[176:177]
	v_pk_fma_f32 v[98:99], v[22:23], v[74:75], v[98:99]
	v_pk_fma_f32 v[176:177], v[24:25], v[70:71], v[176:177]
	v_pk_fma_f32 v[98:99], v[26:27], v[72:73], v[98:99]
	v_pk_fma_f32 v[176:177], v[34:35], v[130:131], v[176:177]
	v_pk_fma_f32 v[98:99], v[36:37], v[132:133], v[98:99]
	v_pk_fma_f32 v[176:177], v[38:39], v[128:129], v[176:177]
	v_pk_fma_f32 v[98:99], v[40:41], v[126:127], v[98:99]
	v_pk_fma_f32 v[176:177], v[58:59], v[124:125], v[176:177]
	v_pk_fma_f32 v[98:99], v[42:43], v[122:123], v[98:99]
	v_pk_fma_f32 v[176:177], v[44:45], v[120:121], v[176:177]
	v_pk_fma_f32 v[98:99], v[46:47], v[118:119], v[98:99]
	v_pk_fma_f32 v[176:177], v[60:61], v[116:117], v[176:177]
	v_pk_fma_f32 v[98:99], v[48:49], v[114:115], v[98:99]
	v_pk_fma_f32 v[176:177], v[50:51], v[112:113], v[176:177]
	v_pk_fma_f32 v[98:99], v[52:53], v[110:111], v[98:99]
	v_pk_fma_f32 v[176:177], v[62:63], v[108:109], v[176:177]
	v_pk_fma_f32 v[98:99], v[54:55], v[106:107], v[98:99]
	v_pk_fma_f32 v[176:177], v[56:57], v[104:105], v[176:177]
	v_pk_fma_f32 v[98:99], v[64:65], v[102:103], v[98:99]
	s_nop 0
	v_pk_add_f32 v[98:99], v[98:99], v[176:177]
	ds_write_b64 v100, v[98:99]
	v_lshlrev_b32_e32 v100, 16, v158
	s_and_b64 vcc, exec, s[0:1]
	v_and_b32_e32 v101, 0xffff0000, v158
	s_cbranch_vccz .LBB0_1117

.LBB0_1149:
	v_pk_fma_f32 v[94:95], v[4:5], v[94:95], v[66:67]
	v_lshl_add_u32 v96, s35, 11, v139
	v_pk_mul_f32 v[176:177], v[6:7], v[92:93]
	v_add3_u32 v96, v96, v2, s64
	v_pk_fma_f32 v[94:95], v[8:9], v[90:91], v[94:95]
	v_pk_fma_f32 v[176:177], v[28:29], v[88:89], v[176:177]
	v_pk_fma_f32 v[94:95], v[10:11], v[86:87], v[94:95]
	v_pk_fma_f32 v[176:177], v[12:13], v[84:85], v[176:177]
	v_pk_fma_f32 v[94:95], v[14:15], v[82:83], v[94:95]
	v_pk_fma_f32 v[176:177], v[30:31], v[80:81], v[176:177]
	v_pk_fma_f32 v[94:95], v[16:17], v[78:79], v[94:95]
	v_pk_fma_f32 v[176:177], v[18:19], v[76:77], v[176:177]
	v_pk_fma_f32 v[94:95], v[20:21], v[74:75], v[94:95]
	v_pk_fma_f32 v[176:177], v[32:33], v[70:71], v[176:177]
	v_pk_fma_f32 v[94:95], v[22:23], v[72:73], v[94:95]
	v_pk_fma_f32 v[176:177], v[24:25], v[130:131], v[176:177]
	v_pk_fma_f32 v[94:95], v[26:27], v[132:133], v[94:95]
	v_pk_fma_f32 v[176:177], v[34:35], v[128:129], v[176:177]
	v_pk_fma_f32 v[94:95], v[36:37], v[126:127], v[94:95]
	v_pk_fma_f32 v[176:177], v[38:39], v[124:125], v[176:177]
	v_pk_fma_f32 v[94:95], v[40:41], v[122:123], v[94:95]
	v_pk_fma_f32 v[176:177], v[58:59], v[120:121], v[176:177]
	v_pk_fma_f32 v[94:95], v[42:43], v[118:119], v[94:95]
	v_pk_fma_f32 v[176:177], v[44:45], v[116:117], v[176:177]
	v_pk_fma_f32 v[94:95], v[46:47], v[114:115], v[94:95]
	v_pk_fma_f32 v[176:177], v[60:61], v[112:113], v[176:177]
	v_pk_fma_f32 v[94:95], v[48:49], v[110:111], v[94:95]
	v_pk_fma_f32 v[176:177], v[50:51], v[108:109], v[176:177]
	v_pk_fma_f32 v[94:95], v[52:53], v[106:107], v[94:95]
	v_pk_fma_f32 v[176:177], v[62:63], v[104:105], v[176:177]
	v_pk_fma_f32 v[94:95], v[54:55], v[102:103], v[94:95]
	v_pk_fma_f32 v[176:177], v[56:57], v[100:101], v[176:177]
	v_pk_fma_f32 v[94:95], v[64:65], v[98:99], v[94:95]
	s_nop 0
	v_pk_add_f32 v[94:95], v[94:95], v[176:177]
	ds_write_b64 v96, v[94:95]
	v_lshlrev_b32_e32 v96, 16, v156
	s_and_b64 vcc, exec, s[0:1]
	v_and_b32_e32 v97, 0xffff0000, v156
	s_cbranch_vccz .LBB0_1119

.LBB0_1151:
	v_pk_fma_f32 v[90:91], v[4:5], v[90:91], v[66:67]
	v_lshl_add_u32 v92, s33, 11, v139
	v_pk_mul_f32 v[176:177], v[6:7], v[88:89]
	v_add3_u32 v92, v92, v2, s64
	v_pk_fma_f32 v[90:91], v[8:9], v[86:87], v[90:91]
	v_pk_fma_f32 v[176:177], v[28:29], v[84:85], v[176:177]
	v_pk_fma_f32 v[90:91], v[10:11], v[82:83], v[90:91]
	v_pk_fma_f32 v[176:177], v[12:13], v[80:81], v[176:177]
	v_pk_fma_f32 v[90:91], v[14:15], v[78:79], v[90:91]
	v_pk_fma_f32 v[176:177], v[30:31], v[76:77], v[176:177]
	v_pk_fma_f32 v[90:91], v[16:17], v[74:75], v[90:91]
	v_pk_fma_f32 v[176:177], v[18:19], v[70:71], v[176:177]
	v_pk_fma_f32 v[90:91], v[20:21], v[72:73], v[90:91]
	v_pk_fma_f32 v[176:177], v[32:33], v[130:131], v[176:177]
	v_pk_fma_f32 v[90:91], v[22:23], v[132:133], v[90:91]
	v_pk_fma_f32 v[176:177], v[24:25], v[128:129], v[176:177]
	v_pk_fma_f32 v[90:91], v[26:27], v[126:127], v[90:91]
	v_pk_fma_f32 v[176:177], v[34:35], v[124:125], v[176:177]
	v_pk_fma_f32 v[90:91], v[36:37], v[122:123], v[90:91]
	v_pk_fma_f32 v[176:177], v[38:39], v[120:121], v[176:177]
	v_pk_fma_f32 v[90:91], v[40:41], v[118:119], v[90:91]
	v_pk_fma_f32 v[176:177], v[58:59], v[116:117], v[176:177]
	v_pk_fma_f32 v[90:91], v[42:43], v[114:115], v[90:91]
	v_pk_fma_f32 v[176:177], v[44:45], v[112:113], v[176:177]
	v_pk_fma_f32 v[90:91], v[46:47], v[110:111], v[90:91]
	v_pk_fma_f32 v[176:177], v[60:61], v[108:109], v[176:177]
	v_pk_fma_f32 v[90:91], v[48:49], v[106:107], v[90:91]
	v_pk_fma_f32 v[176:177], v[50:51], v[104:105], v[176:177]
	v_pk_fma_f32 v[90:91], v[52:53], v[102:103], v[90:91]
	v_pk_fma_f32 v[176:177], v[62:63], v[100:101], v[176:177]
	v_pk_fma_f32 v[90:91], v[54:55], v[98:99], v[90:91]
	v_pk_fma_f32 v[176:177], v[56:57], v[96:97], v[176:177]
	v_pk_fma_f32 v[90:91], v[64:65], v[94:95], v[90:91]
	s_nop 0
	v_pk_add_f32 v[90:91], v[90:91], v[176:177]
	ds_write_b64 v92, v[90:91]
	v_lshlrev_b32_e32 v92, 16, v154
	s_and_b64 vcc, exec, s[0:1]
	v_and_b32_e32 v93, 0xffff0000, v154
	s_cbranch_vccz .LBB0_1121

.LBB0_1153:
	v_pk_fma_f32 v[86:87], v[4:5], v[86:87], v[66:67]
	v_lshl_add_u32 v88, s30, 11, v139
	v_pk_mul_f32 v[176:177], v[6:7], v[84:85]
	v_add3_u32 v88, v88, v2, s64
	v_pk_fma_f32 v[86:87], v[8:9], v[82:83], v[86:87]
	v_pk_fma_f32 v[176:177], v[28:29], v[80:81], v[176:177]
	v_pk_fma_f32 v[86:87], v[10:11], v[78:79], v[86:87]
	v_pk_fma_f32 v[176:177], v[12:13], v[76:77], v[176:177]
	v_pk_fma_f32 v[86:87], v[14:15], v[74:75], v[86:87]
	v_pk_fma_f32 v[176:177], v[30:31], v[70:71], v[176:177]
	v_pk_fma_f32 v[86:87], v[16:17], v[72:73], v[86:87]
	v_pk_fma_f32 v[176:177], v[18:19], v[130:131], v[176:177]
	v_pk_fma_f32 v[86:87], v[20:21], v[132:133], v[86:87]
	v_pk_fma_f32 v[176:177], v[32:33], v[128:129], v[176:177]
	v_pk_fma_f32 v[86:87], v[22:23], v[126:127], v[86:87]
	v_pk_fma_f32 v[176:177], v[24:25], v[124:125], v[176:177]
	v_pk_fma_f32 v[86:87], v[26:27], v[122:123], v[86:87]
	v_pk_fma_f32 v[176:177], v[34:35], v[120:121], v[176:177]
	v_pk_fma_f32 v[86:87], v[36:37], v[118:119], v[86:87]
	v_pk_fma_f32 v[176:177], v[38:39], v[116:117], v[176:177]
	v_pk_fma_f32 v[86:87], v[40:41], v[114:115], v[86:87]
	v_pk_fma_f32 v[176:177], v[58:59], v[112:113], v[176:177]
	v_pk_fma_f32 v[86:87], v[42:43], v[110:111], v[86:87]
	v_pk_fma_f32 v[176:177], v[44:45], v[108:109], v[176:177]
	v_pk_fma_f32 v[86:87], v[46:47], v[106:107], v[86:87]
	v_pk_fma_f32 v[176:177], v[60:61], v[104:105], v[176:177]
	v_pk_fma_f32 v[86:87], v[48:49], v[102:103], v[86:87]
	v_pk_fma_f32 v[176:177], v[50:51], v[100:101], v[176:177]
	v_pk_fma_f32 v[86:87], v[52:53], v[98:99], v[86:87]
	v_pk_fma_f32 v[176:177], v[62:63], v[96:97], v[176:177]
	v_pk_fma_f32 v[86:87], v[54:55], v[94:95], v[86:87]
	v_pk_fma_f32 v[176:177], v[56:57], v[92:93], v[176:177]
	v_pk_fma_f32 v[86:87], v[64:65], v[90:91], v[86:87]
	s_nop 0
	v_pk_add_f32 v[86:87], v[86:87], v[176:177]
	ds_write_b64 v88, v[86:87]
	v_lshlrev_b32_e32 v88, 16, v152
	s_and_b64 vcc, exec, s[0:1]
	v_and_b32_e32 v89, 0xffff0000, v152
	s_cbranch_vccz .LBB0_1123

.LBB0_1155:
	v_pk_fma_f32 v[82:83], v[4:5], v[82:83], v[66:67]
	v_lshl_add_u32 v84, s28, 11, v139
	v_pk_mul_f32 v[176:177], v[6:7], v[80:81]
	v_add3_u32 v84, v84, v2, s64
	v_pk_fma_f32 v[82:83], v[8:9], v[78:79], v[82:83]
	v_pk_fma_f32 v[176:177], v[28:29], v[76:77], v[176:177]
	v_pk_fma_f32 v[82:83], v[10:11], v[74:75], v[82:83]
	v_pk_fma_f32 v[176:177], v[12:13], v[70:71], v[176:177]
	v_pk_fma_f32 v[82:83], v[14:15], v[72:73], v[82:83]
	v_pk_fma_f32 v[176:177], v[30:31], v[130:131], v[176:177]
	v_pk_fma_f32 v[82:83], v[16:17], v[132:133], v[82:83]
	v_pk_fma_f32 v[176:177], v[18:19], v[128:129], v[176:177]
	v_pk_fma_f32 v[82:83], v[20:21], v[126:127], v[82:83]
	v_pk_fma_f32 v[176:177], v[32:33], v[124:125], v[176:177]
	v_pk_fma_f32 v[82:83], v[22:23], v[122:123], v[82:83]
	v_pk_fma_f32 v[176:177], v[24:25], v[120:121], v[176:177]
	v_pk_fma_f32 v[82:83], v[26:27], v[118:119], v[82:83]
	v_pk_fma_f32 v[176:177], v[34:35], v[116:117], v[176:177]
	v_pk_fma_f32 v[82:83], v[36:37], v[114:115], v[82:83]
	v_pk_fma_f32 v[176:177], v[38:39], v[112:113], v[176:177]
	v_pk_fma_f32 v[82:83], v[40:41], v[110:111], v[82:83]
	v_pk_fma_f32 v[176:177], v[58:59], v[108:109], v[176:177]
	v_pk_fma_f32 v[82:83], v[42:43], v[106:107], v[82:83]
	v_pk_fma_f32 v[176:177], v[44:45], v[104:105], v[176:177]
	v_pk_fma_f32 v[82:83], v[46:47], v[102:103], v[82:83]
	v_pk_fma_f32 v[176:177], v[60:61], v[100:101], v[176:177]
	v_pk_fma_f32 v[82:83], v[48:49], v[98:99], v[82:83]
	v_pk_fma_f32 v[176:177], v[50:51], v[96:97], v[176:177]
	v_pk_fma_f32 v[82:83], v[52:53], v[94:95], v[82:83]
	v_pk_fma_f32 v[176:177], v[62:63], v[92:93], v[176:177]
	v_pk_fma_f32 v[82:83], v[54:55], v[90:91], v[82:83]
	v_pk_fma_f32 v[176:177], v[56:57], v[88:89], v[176:177]
	v_pk_fma_f32 v[82:83], v[64:65], v[86:87], v[82:83]
	s_nop 0
	v_pk_add_f32 v[82:83], v[82:83], v[176:177]
	ds_write_b64 v84, v[82:83]
	v_lshlrev_b32_e32 v84, 16, v150
	s_and_b64 vcc, exec, s[0:1]
	v_and_b32_e32 v85, 0xffff0000, v150
	s_cbranch_vccz .LBB0_1125

.LBB0_1157:
	v_pk_fma_f32 v[78:79], v[4:5], v[78:79], v[66:67]
	v_lshl_add_u32 v80, s26, 11, v139
	v_pk_mul_f32 v[176:177], v[6:7], v[76:77]
	v_add3_u32 v80, v80, v2, s64
	v_pk_fma_f32 v[78:79], v[8:9], v[74:75], v[78:79]
	v_pk_fma_f32 v[176:177], v[28:29], v[70:71], v[176:177]
	v_pk_fma_f32 v[78:79], v[10:11], v[72:73], v[78:79]
	v_pk_fma_f32 v[176:177], v[12:13], v[130:131], v[176:177]
	v_pk_fma_f32 v[78:79], v[14:15], v[132:133], v[78:79]
	v_pk_fma_f32 v[176:177], v[30:31], v[128:129], v[176:177]
	v_pk_fma_f32 v[78:79], v[16:17], v[126:127], v[78:79]
	v_pk_fma_f32 v[176:177], v[18:19], v[124:125], v[176:177]
	v_pk_fma_f32 v[78:79], v[20:21], v[122:123], v[78:79]
	v_pk_fma_f32 v[176:177], v[32:33], v[120:121], v[176:177]
	v_pk_fma_f32 v[78:79], v[22:23], v[118:119], v[78:79]
	v_pk_fma_f32 v[176:177], v[24:25], v[116:117], v[176:177]
	v_pk_fma_f32 v[78:79], v[26:27], v[114:115], v[78:79]
	v_pk_fma_f32 v[176:177], v[34:35], v[112:113], v[176:177]
	v_pk_fma_f32 v[78:79], v[36:37], v[110:111], v[78:79]
	v_pk_fma_f32 v[176:177], v[38:39], v[108:109], v[176:177]
	v_pk_fma_f32 v[78:79], v[40:41], v[106:107], v[78:79]
	v_pk_fma_f32 v[176:177], v[58:59], v[104:105], v[176:177]
	v_pk_fma_f32 v[78:79], v[42:43], v[102:103], v[78:79]
	v_pk_fma_f32 v[176:177], v[44:45], v[100:101], v[176:177]
	v_pk_fma_f32 v[78:79], v[46:47], v[98:99], v[78:79]
	v_pk_fma_f32 v[176:177], v[60:61], v[96:97], v[176:177]
	v_pk_fma_f32 v[78:79], v[48:49], v[94:95], v[78:79]
	v_pk_fma_f32 v[176:177], v[50:51], v[92:93], v[176:177]
	v_pk_fma_f32 v[78:79], v[52:53], v[90:91], v[78:79]
	v_pk_fma_f32 v[176:177], v[62:63], v[88:89], v[176:177]
	v_pk_fma_f32 v[78:79], v[54:55], v[86:87], v[78:79]
	v_pk_fma_f32 v[176:177], v[56:57], v[84:85], v[176:177]
	v_pk_fma_f32 v[78:79], v[64:65], v[82:83], v[78:79]
	s_nop 0
	v_pk_add_f32 v[78:79], v[78:79], v[176:177]
	ds_write_b64 v80, v[78:79]
	v_lshlrev_b32_e32 v80, 16, v148
	s_and_b64 vcc, exec, s[0:1]
	v_and_b32_e32 v81, 0xffff0000, v148
	s_cbranch_vccz .LBB0_1127

.LBB0_1159:
	v_pk_fma_f32 v[74:75], v[4:5], v[74:75], v[66:67]
	v_lshl_add_u32 v76, s24, 11, v139
	v_pk_mul_f32 v[176:177], v[6:7], v[70:71]
	v_add3_u32 v76, v76, v2, s64
	v_pk_fma_f32 v[74:75], v[8:9], v[72:73], v[74:75]
	v_pk_fma_f32 v[176:177], v[28:29], v[130:131], v[176:177]
	v_pk_fma_f32 v[74:75], v[10:11], v[132:133], v[74:75]
	v_pk_fma_f32 v[176:177], v[12:13], v[128:129], v[176:177]
	v_pk_fma_f32 v[74:75], v[14:15], v[126:127], v[74:75]
	v_pk_fma_f32 v[176:177], v[30:31], v[124:125], v[176:177]
	v_pk_fma_f32 v[74:75], v[16:17], v[122:123], v[74:75]
	v_pk_fma_f32 v[176:177], v[18:19], v[120:121], v[176:177]
	v_pk_fma_f32 v[74:75], v[20:21], v[118:119], v[74:75]
	v_pk_fma_f32 v[176:177], v[32:33], v[116:117], v[176:177]
	v_pk_fma_f32 v[74:75], v[22:23], v[114:115], v[74:75]
	v_pk_fma_f32 v[176:177], v[24:25], v[112:113], v[176:177]
	v_pk_fma_f32 v[74:75], v[26:27], v[110:111], v[74:75]
	v_pk_fma_f32 v[176:177], v[34:35], v[108:109], v[176:177]
	v_pk_fma_f32 v[74:75], v[36:37], v[106:107], v[74:75]
	v_pk_fma_f32 v[176:177], v[38:39], v[104:105], v[176:177]
	v_pk_fma_f32 v[74:75], v[40:41], v[102:103], v[74:75]
	v_pk_fma_f32 v[176:177], v[58:59], v[100:101], v[176:177]
	v_pk_fma_f32 v[74:75], v[42:43], v[98:99], v[74:75]
	v_pk_fma_f32 v[176:177], v[44:45], v[96:97], v[176:177]
	v_pk_fma_f32 v[74:75], v[46:47], v[94:95], v[74:75]
	v_pk_fma_f32 v[176:177], v[60:61], v[92:93], v[176:177]
	v_pk_fma_f32 v[74:75], v[48:49], v[90:91], v[74:75]
	v_pk_fma_f32 v[176:177], v[50:51], v[88:89], v[176:177]
	v_pk_fma_f32 v[74:75], v[52:53], v[86:87], v[74:75]
	v_pk_fma_f32 v[176:177], v[62:63], v[84:85], v[176:177]
	v_pk_fma_f32 v[74:75], v[54:55], v[82:83], v[74:75]
	v_pk_fma_f32 v[176:177], v[56:57], v[80:81], v[176:177]
	v_pk_fma_f32 v[74:75], v[64:65], v[78:79], v[74:75]
	s_nop 0
	v_pk_add_f32 v[74:75], v[74:75], v[176:177]
	ds_write_b64 v76, v[74:75]
	v_lshlrev_b32_e32 v76, 16, v144
	s_and_b64 vcc, exec, s[0:1]
	v_and_b32_e32 v77, 0xffff0000, v144
	s_cbranch_vccz .LBB0_1129

.LBB0_1161:
	v_pk_fma_f32 v[70:71], v[4:5], v[72:73], v[66:67]
	v_pk_mul_f32 v[176:177], v[6:7], v[130:131]
	v_pk_fma_f32 v[70:71], v[8:9], v[132:133], v[70:71]
	v_pk_fma_f32 v[176:177], v[28:29], v[128:129], v[176:177]
	v_pk_fma_f32 v[70:71], v[10:11], v[126:127], v[70:71]
	v_pk_fma_f32 v[176:177], v[12:13], v[124:125], v[176:177]
	v_pk_fma_f32 v[70:71], v[14:15], v[122:123], v[70:71]
	v_pk_fma_f32 v[176:177], v[30:31], v[120:121], v[176:177]
	v_pk_fma_f32 v[70:71], v[16:17], v[118:119], v[70:71]
	v_pk_fma_f32 v[176:177], v[18:19], v[116:117], v[176:177]
	v_pk_fma_f32 v[70:71], v[20:21], v[114:115], v[70:71]
	v_pk_fma_f32 v[176:177], v[32:33], v[112:113], v[176:177]
	v_pk_fma_f32 v[70:71], v[22:23], v[110:111], v[70:71]
	v_pk_fma_f32 v[176:177], v[24:25], v[108:109], v[176:177]
	v_pk_fma_f32 v[70:71], v[26:27], v[106:107], v[70:71]
	v_pk_fma_f32 v[176:177], v[34:35], v[104:105], v[176:177]
	v_pk_fma_f32 v[70:71], v[36:37], v[102:103], v[70:71]
	v_pk_fma_f32 v[176:177], v[38:39], v[100:101], v[176:177]
	v_pk_fma_f32 v[70:71], v[40:41], v[98:99], v[70:71]
	v_pk_fma_f32 v[176:177], v[58:59], v[96:97], v[176:177]
	v_pk_fma_f32 v[70:71], v[42:43], v[94:95], v[70:71]
	v_pk_fma_f32 v[176:177], v[44:45], v[92:93], v[176:177]
	v_pk_fma_f32 v[70:71], v[46:47], v[90:91], v[70:71]
	v_pk_fma_f32 v[176:177], v[60:61], v[88:89], v[176:177]
	v_pk_fma_f32 v[70:71], v[48:49], v[86:87], v[70:71]
	v_pk_fma_f32 v[176:177], v[50:51], v[84:85], v[176:177]
	v_pk_fma_f32 v[70:71], v[52:53], v[82:83], v[70:71]
	v_pk_fma_f32 v[176:177], v[62:63], v[80:81], v[176:177]
	v_pk_fma_f32 v[70:71], v[54:55], v[78:79], v[70:71]
	v_pk_fma_f32 v[176:177], v[56:57], v[76:77], v[176:177]
	v_pk_fma_f32 v[70:71], v[64:65], v[74:75], v[70:71]
	s_nop 0
	v_pk_add_f32 v[70:71], v[70:71], v[176:177]
	ds_write_b64 v140, v[70:71] offset:63488
	v_lshlrev_b32_e32 v70, 16, v141
	s_andn2_b64 vcc, exec, s[14:15]
	v_and_b32_e32 v71, 0xffff0000, v141
	s_cbranch_vccz .LBB0_1131

.LBB0_1163:
	v_pk_fma_f32 v[130:131], v[4:5], v[132:133], v[66:67]
	v_lshl_add_u32 v132, s22, 11, v139
	v_pk_mul_f32 v[176:177], v[6:7], v[128:129]
	v_add3_u32 v132, v132, v2, s64
	v_pk_fma_f32 v[130:131], v[8:9], v[126:127], v[130:131]
	v_pk_fma_f32 v[176:177], v[28:29], v[124:125], v[176:177]
	v_pk_fma_f32 v[130:131], v[10:11], v[122:123], v[130:131]
	v_pk_fma_f32 v[176:177], v[12:13], v[120:121], v[176:177]
	v_pk_fma_f32 v[130:131], v[14:15], v[118:119], v[130:131]
	v_pk_fma_f32 v[176:177], v[30:31], v[116:117], v[176:177]
	v_pk_fma_f32 v[130:131], v[16:17], v[114:115], v[130:131]
	v_pk_fma_f32 v[176:177], v[18:19], v[112:113], v[176:177]
	v_pk_fma_f32 v[130:131], v[20:21], v[110:111], v[130:131]
	v_pk_fma_f32 v[176:177], v[32:33], v[108:109], v[176:177]
	v_pk_fma_f32 v[130:131], v[22:23], v[106:107], v[130:131]
	v_pk_fma_f32 v[176:177], v[24:25], v[104:105], v[176:177]
	v_pk_fma_f32 v[130:131], v[26:27], v[102:103], v[130:131]
	v_pk_fma_f32 v[176:177], v[34:35], v[100:101], v[176:177]
	v_pk_fma_f32 v[130:131], v[36:37], v[98:99], v[130:131]
	v_pk_fma_f32 v[176:177], v[38:39], v[96:97], v[176:177]
	v_pk_fma_f32 v[130:131], v[40:41], v[94:95], v[130:131]
	v_pk_fma_f32 v[176:177], v[58:59], v[92:93], v[176:177]
	v_pk_fma_f32 v[130:131], v[42:43], v[90:91], v[130:131]
	v_pk_fma_f32 v[176:177], v[44:45], v[88:89], v[176:177]
	v_pk_fma_f32 v[130:131], v[46:47], v[86:87], v[130:131]
	v_pk_fma_f32 v[176:177], v[60:61], v[84:85], v[176:177]
	v_pk_fma_f32 v[130:131], v[48:49], v[82:83], v[130:131]
	v_pk_fma_f32 v[176:177], v[50:51], v[80:81], v[176:177]
	v_pk_fma_f32 v[130:131], v[52:53], v[78:79], v[130:131]
	v_pk_fma_f32 v[176:177], v[62:63], v[76:77], v[176:177]
	v_pk_fma_f32 v[130:131], v[54:55], v[74:75], v[130:131]
	v_pk_fma_f32 v[176:177], v[56:57], v[70:71], v[176:177]
	v_pk_fma_f32 v[130:131], v[64:65], v[72:73], v[130:131]
	s_nop 0
	v_pk_add_f32 v[130:131], v[130:131], v[176:177]
	ds_write_b64 v132, v[130:131]
	s_branch .LBB0_1035
